# opt38: opt26 + back-edge rotation: K-loop counter/pointer bump/exit test moved in front of the loop-closing barrier (7 GEMM loops + diff-attention loop)
# baseline (speedup 1.0000x reference)
; #define PG8_STAGE(bufoff, gbase, voff) do { _Pragma("unroll") for (int _i = 0; _i < 2; ++_i) \
;         __builtin_amdgcn_global_load_lds((const unsigned*)((const char*)(gbase) + (voff)[_i]), (LAS unsigned*)(lds + (bufoff) + ldsw + _i * 8192), 16, 0, 0); } while (0)
; #define PG8_LDA(dst, b, h) do { _Pragma("unroll") for (int m = 0; m < 4; ++m) _Pragma("unroll") for (int k = 0; k < 2; ++k) dst[m][k] = *(const LAS bf16x8*)(lds + PG8_SA(b, h) + aoff + m * 2048 + k * 1024); } while (0)
; #define PG8_LDB(dst, b, h) do { _Pragma("unroll") for (int n = 0; n < 2; ++n) _Pragma("unroll") for (int k = 0; k < 2; ++k) dst[n][k] = *(const LAS bf16x8*)(lds + PG8_SB(b, h) + boff + n * 2048 + k * 1024); } while (0)
; #define PG8_MMA(ai, bj, At, Bt) do { __builtin_amdgcn_s_setprio(1); _Pragma("unroll") for (int m = 0; m < 4; ++m) _Pragma("unroll") for (int n = 0; n < 2; ++n) _Pragma("unroll") for (int k = 0; k < 2; ++k) \
;         acc[ai][bj][m][n] = __builtin_amdgcn_mfma_f32_16x16x32_bf16(Bt[n][k], At[m][k], acc[ai][bj][m][n], 0, 0, 0); __builtin_amdgcn_s_setprio(0); } while (0)
; #define PG8_WAIT_V(n) asm volatile("s_waitcnt vmcnt(" #n ")" ::: "memory")
; #define PG8_WAIT_L(n) asm volatile("s_waitcnt lgkmcnt(" #n ")" ::: "memory")
; #define PG8_BAR __builtin_amdgcn_s_barrier()
; #define PG8_SCHED __builtin_amdgcn_sched_barrier(0)
; template <class Epi>
; __device__ __forceinline__ void gemm_phase(LAS unsigned char* lds, const Gemm g, const StaticOrder& S, const Epi& E) {
;     ...
;             PG8_LDB(B0, 0, 0); PG8_LDB(B1, 0, 1); PG8_SCHED; PG8_LDA(At, 0, 0); PG8_STAGE(PG8_SA(1, 1), a1 + hsA, voffA);
;             PG8_WAIT_V(8); PG8_WAIT_L(0); PG8_BAR; PG8_MMA(0, 0, At, B0); PG8_MMA(0, 1, At, B1); PG8_BAR; PG8_SCHED;
;             PG8_LDA(At, 0, 1); PG8_STAGE(PG8_SB(0, 0), b2, voffB); PG8_STAGE(PG8_SB(0, 1), b2 + hsB, voffB); PG8_STAGE(PG8_SA(0, 0), a2, voffA);
;             PG8_WAIT_V(8); PG8_WAIT_L(0); PG8_BAR; PG8_MMA(1, 0, At, B0); PG8_MMA(1, 1, At, B1); PG8_BAR; PG8_SCHED;
.LBB0_214:
	ds_read_b128 v[144:147], v155
	ds_read_b128 v[148:151], v155 offset:1024
	ds_read_b128 v[162:165], v155 offset:2048
	ds_read_b128 v[166:169], v155 offset:3072
	ds_read_b128 v[180:183], v156
	ds_read_b128 v[184:187], v156 offset:1024
	ds_read_b128 v[188:191], v156 offset:2048
	ds_read_b128 v[192:195], v156 offset:3072
	s_add_u32 s38, s58, 0xfffc0080
	s_addc_u32 s39, s59, -1
	s_cmp_eq_u32 s37, 12
	s_cselect_b32 s63, s6, s39
	s_cselect_b32 s62, s7, s38
	s_cselect_b32 s61, s11, s36
	s_cselect_b32 s60, s13, s35
	s_add_i32 m0, s19, 0xc000
	ds_read_b128 v[196:199], v157
	ds_read_b128 v[200:203], v157 offset:1024
	ds_read_b128 v[204:207], v157 offset:2048
	ds_read_b128 v[208:211], v157 offset:3072
	ds_read_b128 v[212:215], v157 offset:4096
	ds_read_b128 v[216:219], v157 offset:5120
	ds_read_b128 v[220:223], v157 offset:6144
	ds_read_b128 v[224:227], v157 offset:7168
	global_load_lds_dwordx4 v136, s[58:59]
	s_add_i32 m0, s19, 0xe000
	s_nop 0
	global_load_lds_dwordx4 v138, s[58:59]
	s_waitcnt vmcnt(8)
	s_waitcnt lgkmcnt(0)
	s_barrier
	s_setprio 1
	s_waitcnt lgkmcnt(0)
	v_mfma_f32_16x16x32_bf16 v[124:127], v[144:147], v[196:199], v[124:127]
	v_mfma_f32_16x16x32_bf16 v[120:123], v[162:165], v[196:199], v[120:123]
	v_mfma_f32_16x16x32_bf16 v[108:111], v[144:147], v[204:207], v[108:111]
	v_mfma_f32_16x16x32_bf16 v[104:107], v[162:165], v[204:207], v[104:107]
	v_mfma_f32_16x16x32_bf16 v[92:95], v[144:147], v[212:215], v[92:95]
	v_mfma_f32_16x16x32_bf16 v[88:91], v[162:165], v[212:215], v[88:91]
	v_mfma_f32_16x16x32_bf16 v[76:79], v[144:147], v[220:223], v[76:79]
	v_mfma_f32_16x16x32_bf16 v[72:75], v[162:165], v[220:223], v[72:75]
	v_mfma_f32_16x16x32_bf16 v[124:127], v[148:151], v[200:203], v[124:127]
	v_mfma_f32_16x16x32_bf16 v[120:123], v[166:169], v[200:203], v[120:123]
	v_mfma_f32_16x16x32_bf16 v[108:111], v[148:151], v[208:211], v[108:111]
	v_mfma_f32_16x16x32_bf16 v[104:107], v[166:169], v[208:211], v[104:107]
	v_mfma_f32_16x16x32_bf16 v[92:95], v[148:151], v[216:219], v[92:95]
	v_mfma_f32_16x16x32_bf16 v[88:91], v[166:169], v[216:219], v[88:91]
	v_mfma_f32_16x16x32_bf16 v[76:79], v[148:151], v[224:227], v[76:79]
	v_mfma_f32_16x16x32_bf16 v[72:75], v[166:169], v[224:227], v[72:75]
	s_setprio 0
	s_setprio 1
	v_mfma_f32_16x16x32_bf16 v[116:119], v[180:183], v[196:199], v[116:119]
	v_mfma_f32_16x16x32_bf16 v[112:115], v[188:191], v[196:199], v[112:115]
	v_mfma_f32_16x16x32_bf16 v[100:103], v[180:183], v[204:207], v[100:103]
	v_mfma_f32_16x16x32_bf16 v[96:99], v[188:191], v[204:207], v[96:99]
	v_mfma_f32_16x16x32_bf16 v[84:87], v[180:183], v[212:215], v[84:87]
	v_mfma_f32_16x16x32_bf16 v[80:83], v[188:191], v[212:215], v[80:83]
	v_mfma_f32_16x16x32_bf16 v[68:71], v[180:183], v[220:223], v[68:71]
	v_mfma_f32_16x16x32_bf16 v[64:67], v[188:191], v[220:223], v[64:67]
	v_mfma_f32_16x16x32_bf16 v[116:119], v[184:187], v[200:203], v[116:119]
	v_mfma_f32_16x16x32_bf16 v[112:115], v[192:195], v[200:203], v[112:115]
	v_mfma_f32_16x16x32_bf16 v[100:103], v[184:187], v[208:211], v[100:103]
	v_mfma_f32_16x16x32_bf16 v[96:99], v[192:195], v[208:211], v[96:99]
	v_mfma_f32_16x16x32_bf16 v[84:87], v[184:187], v[216:219], v[84:87]
	v_mfma_f32_16x16x32_bf16 v[80:83], v[192:195], v[216:219], v[80:83]
	v_mfma_f32_16x16x32_bf16 v[68:71], v[184:187], v[224:227], v[68:71]
	v_mfma_f32_16x16x32_bf16 v[64:67], v[192:195], v[224:227], v[64:67]
	s_setprio 0
	s_barrier
	s_add_i32 s38, s30, s16
	s_mov_b32 m0, s38
	ds_read_b128 v[196:199], v157 offset:16384
	ds_read_b128 v[200:203], v157 offset:17408
	ds_read_b128 v[204:207], v157 offset:18432
	ds_read_b128 v[208:211], v157 offset:19456
	ds_read_b128 v[212:215], v157 offset:20480
	ds_read_b128 v[216:219], v157 offset:21504
	ds_read_b128 v[220:223], v157 offset:22528
	ds_read_b128 v[224:227], v157 offset:23552
	global_load_lds_dwordx4 v132, s[60:61]
	s_add_i32 m0, s38, 0x2000
	s_add_u32 s38, s60, 0x40000
	s_addc_u32 s39, s61, 0
	s_add_i32 s40, s31, s16
	global_load_lds_dwordx4 v128, s[60:61]
	s_mov_b32 m0, s40
	s_nop 0
	global_load_lds_dwordx4 v132, s[38:39]
	s_add_i32 m0, s40, 0x2000
	s_nop 0
	global_load_lds_dwordx4 v128, s[38:39]
	s_mov_b32 m0, s19
	s_nop 0
	global_load_lds_dwordx4 v134, s[62:63]
	s_mov_b32 m0, s22
	s_nop 0
	global_load_lds_dwordx4 v130, s[62:63]
	s_waitcnt vmcnt(8)
	s_waitcnt lgkmcnt(0)
	s_barrier
	s_setprio 1
	s_waitcnt lgkmcnt(0)
	v_mfma_f32_16x16x32_bf16 v[60:63], v[144:147], v[196:199], v[60:63]
	v_mfma_f32_16x16x32_bf16 v[56:59], v[162:165], v[196:199], v[56:59]
	v_mfma_f32_16x16x32_bf16 v[44:47], v[144:147], v[204:207], v[44:47]
	v_mfma_f32_16x16x32_bf16 v[40:43], v[162:165], v[204:207], v[40:43]
	v_mfma_f32_16x16x32_bf16 v[28:31], v[144:147], v[212:215], v[28:31]
	v_mfma_f32_16x16x32_bf16 v[24:27], v[162:165], v[212:215], v[24:27]
	v_mfma_f32_16x16x32_bf16 v[12:15], v[144:147], v[220:223], v[12:15]
	v_mfma_f32_16x16x32_bf16 v[8:11], v[162:165], v[220:223], v[8:11]
	v_mfma_f32_16x16x32_bf16 v[60:63], v[148:151], v[200:203], v[60:63]
	v_mfma_f32_16x16x32_bf16 v[56:59], v[166:169], v[200:203], v[56:59]
	v_mfma_f32_16x16x32_bf16 v[44:47], v[148:151], v[208:211], v[44:47]
	v_mfma_f32_16x16x32_bf16 v[40:43], v[166:169], v[208:211], v[40:43]
	v_mfma_f32_16x16x32_bf16 v[28:31], v[148:151], v[216:219], v[28:31]
	v_mfma_f32_16x16x32_bf16 v[24:27], v[166:169], v[216:219], v[24:27]
	v_mfma_f32_16x16x32_bf16 v[12:15], v[148:151], v[224:227], v[12:15]
	v_mfma_f32_16x16x32_bf16 v[8:11], v[166:169], v[224:227], v[8:11]
	s_setprio 0
	s_setprio 1
	v_mfma_f32_16x16x32_bf16 v[52:55], v[180:183], v[196:199], v[52:55]
	v_mfma_f32_16x16x32_bf16 v[48:51], v[188:191], v[196:199], v[48:51]
	v_mfma_f32_16x16x32_bf16 v[36:39], v[180:183], v[204:207], v[36:39]
	v_mfma_f32_16x16x32_bf16 v[32:35], v[188:191], v[204:207], v[32:35]
	v_mfma_f32_16x16x32_bf16 v[20:23], v[180:183], v[212:215], v[20:23]
	v_mfma_f32_16x16x32_bf16 v[16:19], v[188:191], v[212:215], v[16:19]
	v_mfma_f32_16x16x32_bf16 v[4:7], v[180:183], v[220:223], v[4:7]
	v_mfma_f32_16x16x32_bf16 v[0:3], v[188:191], v[220:223], v[0:3]
	v_mfma_f32_16x16x32_bf16 v[52:55], v[184:187], v[200:203], v[52:55]
	v_mfma_f32_16x16x32_bf16 v[48:51], v[192:195], v[200:203], v[48:51]
	v_mfma_f32_16x16x32_bf16 v[36:39], v[184:187], v[208:211], v[36:39]
	v_mfma_f32_16x16x32_bf16 v[32:35], v[192:195], v[208:211], v[32:35]
	v_mfma_f32_16x16x32_bf16 v[20:23], v[184:187], v[216:219], v[20:23]
	v_mfma_f32_16x16x32_bf16 v[16:19], v[192:195], v[216:219], v[16:19]
	v_mfma_f32_16x16x32_bf16 v[4:7], v[184:187], v[224:227], v[4:7]
	v_mfma_f32_16x16x32_bf16 v[0:3], v[192:195], v[224:227], v[0:3]
	s_setprio 0
	s_barrier
; #define PG8_STAGE(bufoff, gbase, voff) do { _Pragma("unroll") for (int _i = 0; _i < 2; ++_i) \
;         __builtin_amdgcn_global_load_lds((const unsigned*)((const char*)(gbase) + (voff)[_i]), (LAS unsigned*)(lds + (bufoff) + ldsw + _i * 8192), 16, 0, 0); } while (0)
; #define PG8_LDA(dst, b, h) do { _Pragma("unroll") for (int m = 0; m < 4; ++m) _Pragma("unroll") for (int k = 0; k < 2; ++k) dst[m][k] = *(const LAS bf16x8*)(lds + PG8_SA(b, h) + aoff + m * 2048 + k * 1024); } while (0)
; #define PG8_LDB(dst, b, h) do { _Pragma("unroll") for (int n = 0; n < 2; ++n) _Pragma("unroll") for (int k = 0; k < 2; ++k) dst[n][k] = *(const LAS bf16x8*)(lds + PG8_SB(b, h) + boff + n * 2048 + k * 1024); } while (0)
; #define PG8_MMA(ai, bj, At, Bt) do { __builtin_amdgcn_s_setprio(1); _Pragma("unroll") for (int m = 0; m < 4; ++m) _Pragma("unroll") for (int n = 0; n < 2; ++n) _Pragma("unroll") for (int k = 0; k < 2; ++k) \
;         acc[ai][bj][m][n] = __builtin_amdgcn_mfma_f32_16x16x32_bf16(Bt[n][k], At[m][k], acc[ai][bj][m][n], 0, 0, 0); __builtin_amdgcn_s_setprio(0); } while (0)
; #define PG8_WAIT_V(n) asm volatile("s_waitcnt vmcnt(" #n ")" ::: "memory")
; #define PG8_WAIT_L(n) asm volatile("s_waitcnt lgkmcnt(" #n ")" ::: "memory")
; #define PG8_BAR __builtin_amdgcn_s_barrier()
; #define PG8_SCHED __builtin_amdgcn_sched_barrier(0)
; template <class Epi>
; __device__ __forceinline__ void gemm_phase(LAS unsigned char* lds, const Gemm g, const StaticOrder& S, const Epi& E) {
;     ...
;             PG8_LDB(B0, 1, 0); PG8_LDB(B1, 1, 1); PG8_SCHED; PG8_LDA(At, 1, 0); PG8_STAGE(PG8_SA(0, 1), a2 + hsA, voffA);
;             PG8_WAIT_V(8); PG8_WAIT_L(0); PG8_BAR; PG8_MMA(0, 0, At, B0); PG8_MMA(0, 1, At, B1); PG8_BAR; PG8_SCHED;
;             PG8_LDA(At, 1, 1); PG8_STAGE(PG8_SB(1, 0), b3, voffB); PG8_STAGE(PG8_SB(1, 1), b3 + hsB, voffB); PG8_STAGE(PG8_SA(1, 0), a3, voffA);
;             PG8_WAIT_V(8); PG8_WAIT_L(0); PG8_BAR; PG8_MMA(1, 0, At, B0); PG8_MMA(1, 1, At, B1); PG8_BAR; PG8_SCHED;
;         }
	s_add_i32 s40, 0, 0x18000
	v_add_u32_e32 v159, s40, v153
	s_add_i32 s41, 0, 0x1c000
	ds_read_b128 v[144:147], v159
	ds_read_b128 v[148:151], v159 offset:1024
	ds_read_b128 v[162:165], v159 offset:2048
	ds_read_b128 v[166:169], v159 offset:3072
	v_add_u32_e32 v159, s41, v153
	ds_read_b128 v[180:183], v159
	ds_read_b128 v[184:187], v159 offset:1024
	ds_read_b128 v[188:191], v159 offset:2048
	ds_read_b128 v[192:195], v159 offset:3072
	s_add_u32 s38, s62, 0x40000
	s_addc_u32 s39, s63, 0
	s_mov_b32 m0, s23
	ds_read_b128 v[196:199], v157 offset:32768
	ds_read_b128 v[200:203], v157 offset:33792
	ds_read_b128 v[204:207], v157 offset:34816
	ds_read_b128 v[208:211], v157 offset:35840
	ds_read_b128 v[212:215], v157 offset:36864
	ds_read_b128 v[216:219], v157 offset:37888
	ds_read_b128 v[220:223], v157 offset:38912
	ds_read_b128 v[224:227], v157 offset:39936
	global_load_lds_dwordx4 v134, s[38:39]
	s_mov_b32 m0, s24
	s_nop 0
	global_load_lds_dwordx4 v130, s[38:39]
	s_waitcnt vmcnt(8)
	s_waitcnt lgkmcnt(0)
	s_barrier
	s_setprio 1
	s_waitcnt lgkmcnt(0)
	v_mfma_f32_16x16x32_bf16 v[124:127], v[144:147], v[196:199], v[124:127]
	v_mfma_f32_16x16x32_bf16 v[120:123], v[162:165], v[196:199], v[120:123]
	v_mfma_f32_16x16x32_bf16 v[108:111], v[144:147], v[204:207], v[108:111]
	v_mfma_f32_16x16x32_bf16 v[104:107], v[162:165], v[204:207], v[104:107]
	v_mfma_f32_16x16x32_bf16 v[92:95], v[144:147], v[212:215], v[92:95]
	v_mfma_f32_16x16x32_bf16 v[88:91], v[162:165], v[212:215], v[88:91]
	v_mfma_f32_16x16x32_bf16 v[76:79], v[144:147], v[220:223], v[76:79]
	v_mfma_f32_16x16x32_bf16 v[72:75], v[162:165], v[220:223], v[72:75]
	v_mfma_f32_16x16x32_bf16 v[124:127], v[148:151], v[200:203], v[124:127]
	v_mfma_f32_16x16x32_bf16 v[120:123], v[166:169], v[200:203], v[120:123]
	v_mfma_f32_16x16x32_bf16 v[108:111], v[148:151], v[208:211], v[108:111]
	v_mfma_f32_16x16x32_bf16 v[104:107], v[166:169], v[208:211], v[104:107]
	v_mfma_f32_16x16x32_bf16 v[92:95], v[148:151], v[216:219], v[92:95]
	v_mfma_f32_16x16x32_bf16 v[88:91], v[166:169], v[216:219], v[88:91]
	v_mfma_f32_16x16x32_bf16 v[76:79], v[148:151], v[224:227], v[76:79]
	v_mfma_f32_16x16x32_bf16 v[72:75], v[166:169], v[224:227], v[72:75]
	s_setprio 0
	s_setprio 1
	v_mfma_f32_16x16x32_bf16 v[116:119], v[180:183], v[196:199], v[116:119]
	v_mfma_f32_16x16x32_bf16 v[112:115], v[188:191], v[196:199], v[112:115]
	v_mfma_f32_16x16x32_bf16 v[100:103], v[180:183], v[204:207], v[100:103]
	v_mfma_f32_16x16x32_bf16 v[96:99], v[188:191], v[204:207], v[96:99]
	v_mfma_f32_16x16x32_bf16 v[84:87], v[180:183], v[212:215], v[84:87]
	v_mfma_f32_16x16x32_bf16 v[80:83], v[188:191], v[212:215], v[80:83]
	v_mfma_f32_16x16x32_bf16 v[68:71], v[180:183], v[220:223], v[68:71]
	v_mfma_f32_16x16x32_bf16 v[64:67], v[188:191], v[220:223], v[64:67]
	v_mfma_f32_16x16x32_bf16 v[116:119], v[184:187], v[200:203], v[116:119]
	v_mfma_f32_16x16x32_bf16 v[112:115], v[192:195], v[200:203], v[112:115]
	v_mfma_f32_16x16x32_bf16 v[100:103], v[184:187], v[208:211], v[100:103]
	v_mfma_f32_16x16x32_bf16 v[96:99], v[192:195], v[208:211], v[96:99]
	v_mfma_f32_16x16x32_bf16 v[84:87], v[184:187], v[216:219], v[84:87]
	v_mfma_f32_16x16x32_bf16 v[80:83], v[192:195], v[216:219], v[80:83]
	v_mfma_f32_16x16x32_bf16 v[68:71], v[184:187], v[224:227], v[68:71]
	v_mfma_f32_16x16x32_bf16 v[64:67], v[192:195], v[224:227], v[64:67]
	s_setprio 0
	s_barrier
	s_add_u32 s98, s60, 0x80
	s_addc_u32 s99, s61, 0
	s_add_u32 s100, s62, 0x80
	s_addc_u32 s101, s63, 0
	s_add_i32 s38, s40, s16
	s_mov_b32 m0, s38
	ds_read_b128 v[196:199], v157 offset:49152
	ds_read_b128 v[200:203], v157 offset:50176
	ds_read_b128 v[204:207], v157 offset:51200
	ds_read_b128 v[208:211], v157 offset:52224
	ds_read_b128 v[212:215], v157 offset:53248
	ds_read_b128 v[216:219], v157 offset:54272
	ds_read_b128 v[220:223], v157 offset:55296
	ds_read_b128 v[224:227], v157 offset:56320
	global_load_lds_dwordx4 v132, s[98:99]
	s_add_i32 m0, s38, 0x2000
	s_add_u32 s38, s60, 0x40080
	s_addc_u32 s39, s61, 0
	s_add_i32 s40, s41, s16
	global_load_lds_dwordx4 v128, s[98:99]
	s_mov_b32 m0, s40
	s_nop 0
	global_load_lds_dwordx4 v132, s[38:39]
	s_add_i32 m0, s40, 0x2000
	s_nop 0
	global_load_lds_dwordx4 v128, s[38:39]
	s_mov_b32 m0, s25
	s_nop 0
	global_load_lds_dwordx4 v134, s[100:101]
	s_mov_b32 m0, s26
	s_nop 0
	global_load_lds_dwordx4 v130, s[100:101]
	s_waitcnt vmcnt(8)
	s_waitcnt lgkmcnt(0)
	s_barrier
	s_setprio 1
	s_waitcnt lgkmcnt(0)
	v_mfma_f32_16x16x32_bf16 v[60:63], v[144:147], v[196:199], v[60:63]
	v_mfma_f32_16x16x32_bf16 v[56:59], v[162:165], v[196:199], v[56:59]
	v_mfma_f32_16x16x32_bf16 v[44:47], v[144:147], v[204:207], v[44:47]
	v_mfma_f32_16x16x32_bf16 v[40:43], v[162:165], v[204:207], v[40:43]
	v_mfma_f32_16x16x32_bf16 v[28:31], v[144:147], v[212:215], v[28:31]
	v_mfma_f32_16x16x32_bf16 v[24:27], v[162:165], v[212:215], v[24:27]
	v_mfma_f32_16x16x32_bf16 v[12:15], v[144:147], v[220:223], v[12:15]
	v_mfma_f32_16x16x32_bf16 v[8:11], v[162:165], v[220:223], v[8:11]
	v_mfma_f32_16x16x32_bf16 v[60:63], v[148:151], v[200:203], v[60:63]
	v_mfma_f32_16x16x32_bf16 v[56:59], v[166:169], v[200:203], v[56:59]
	v_mfma_f32_16x16x32_bf16 v[44:47], v[148:151], v[208:211], v[44:47]
	v_mfma_f32_16x16x32_bf16 v[40:43], v[166:169], v[208:211], v[40:43]
	v_mfma_f32_16x16x32_bf16 v[28:31], v[148:151], v[216:219], v[28:31]
	v_mfma_f32_16x16x32_bf16 v[24:27], v[166:169], v[216:219], v[24:27]
	v_mfma_f32_16x16x32_bf16 v[12:15], v[148:151], v[224:227], v[12:15]
	v_mfma_f32_16x16x32_bf16 v[8:11], v[166:169], v[224:227], v[8:11]
	s_setprio 0
	s_setprio 1
	v_mfma_f32_16x16x32_bf16 v[52:55], v[180:183], v[196:199], v[52:55]
	v_mfma_f32_16x16x32_bf16 v[48:51], v[188:191], v[196:199], v[48:51]
	v_mfma_f32_16x16x32_bf16 v[36:39], v[180:183], v[204:207], v[36:39]
	v_mfma_f32_16x16x32_bf16 v[32:35], v[188:191], v[204:207], v[32:35]
	v_mfma_f32_16x16x32_bf16 v[20:23], v[180:183], v[212:215], v[20:23]
	v_mfma_f32_16x16x32_bf16 v[16:19], v[188:191], v[212:215], v[16:19]
	v_mfma_f32_16x16x32_bf16 v[4:7], v[180:183], v[220:223], v[4:7]
	v_mfma_f32_16x16x32_bf16 v[0:3], v[188:191], v[220:223], v[0:3]
	v_mfma_f32_16x16x32_bf16 v[52:55], v[184:187], v[200:203], v[52:55]
	v_mfma_f32_16x16x32_bf16 v[48:51], v[192:195], v[200:203], v[48:51]
	v_mfma_f32_16x16x32_bf16 v[36:39], v[184:187], v[208:211], v[36:39]
	v_mfma_f32_16x16x32_bf16 v[32:35], v[192:195], v[208:211], v[32:35]
	v_mfma_f32_16x16x32_bf16 v[20:23], v[184:187], v[216:219], v[20:23]
	v_mfma_f32_16x16x32_bf16 v[16:19], v[192:195], v[216:219], v[16:19]
	v_mfma_f32_16x16x32_bf16 v[4:7], v[184:187], v[224:227], v[4:7]
	v_mfma_f32_16x16x32_bf16 v[0:3], v[192:195], v[224:227], v[0:3]
	s_add_i32 s37, s37, 2
	s_add_u32 s58, s58, 0x100
	s_addc_u32 s59, s59, 0
	s_add_u32 s35, s35, 0x100
	s_addc_u32 s36, s36, 0
	s_cmp_gt_u32 s37, 13
	s_setprio 0
	s_barrier
	s_cbranch_scc0 .LBB0_214
	s_and_b64 vcc, exec, s[8:9]
	s_cbranch_vccz .LBB0_217
	s_barrier

; #define PG8_STAGE(bufoff, gbase, voff) do { _Pragma("unroll") for (int _i = 0; _i < 2; ++_i) \
;         __builtin_amdgcn_global_load_lds((const unsigned*)((const char*)(gbase) + (voff)[_i]), (LAS unsigned*)(lds + (bufoff) + ldsw + _i * 8192), 16, 0, 0); } while (0)
; #define PG8_LDA(dst, b, h) do { _Pragma("unroll") for (int m = 0; m < 4; ++m) _Pragma("unroll") for (int k = 0; k < 2; ++k) dst[m][k] = *(const LAS bf16x8*)(lds + PG8_SA(b, h) + aoff + m * 2048 + k * 1024); } while (0)
; #define PG8_LDB(dst, b, h) do { _Pragma("unroll") for (int n = 0; n < 2; ++n) _Pragma("unroll") for (int k = 0; k < 2; ++k) dst[n][k] = *(const LAS bf16x8*)(lds + PG8_SB(b, h) + boff + n * 2048 + k * 1024); } while (0)
; #define PG8_MMA(ai, bj, At, Bt) do { __builtin_amdgcn_s_setprio(1); _Pragma("unroll") for (int m = 0; m < 4; ++m) _Pragma("unroll") for (int n = 0; n < 2; ++n) _Pragma("unroll") for (int k = 0; k < 2; ++k) \
;         acc[ai][bj][m][n] = __builtin_amdgcn_mfma_f32_16x16x32_bf16(Bt[n][k], At[m][k], acc[ai][bj][m][n], 0, 0, 0); __builtin_amdgcn_s_setprio(0); } while (0)
; #define PG8_WAIT_V(n) asm volatile("s_waitcnt vmcnt(" #n ")" ::: "memory")
; #define PG8_WAIT_L(n) asm volatile("s_waitcnt lgkmcnt(" #n ")" ::: "memory")
; #define PG8_BAR __builtin_amdgcn_s_barrier()
; #define PG8_SCHED __builtin_amdgcn_sched_barrier(0)
; template <class Epi>
; __device__ __forceinline__ void gemm_phase(LAS unsigned char* lds, const Gemm g, const StaticOrder& S, const Epi& E) {
;     ...
;             PG8_LDB(B0, 0, 0); PG8_LDB(B1, 0, 1); PG8_SCHED; PG8_LDA(At, 0, 0); PG8_STAGE(PG8_SA(1, 1), a1 + hsA, voffA);
;             PG8_WAIT_V(8); PG8_WAIT_L(0); PG8_BAR; PG8_MMA(0, 0, At, B0); PG8_MMA(0, 1, At, B1); PG8_BAR; PG8_SCHED;
;             PG8_LDA(At, 0, 1); PG8_STAGE(PG8_SB(0, 0), b2, voffB); PG8_STAGE(PG8_SB(0, 1), b2 + hsB, voffB); PG8_STAGE(PG8_SA(0, 0), a2, voffA);
;             PG8_WAIT_V(8); PG8_WAIT_L(0); PG8_BAR; PG8_MMA(1, 0, At, B0); PG8_MMA(1, 1, At, B1); PG8_BAR; PG8_SCHED;
.LBB0_296:
	ds_read_b128 v[144:147], v157
	ds_read_b128 v[148:151], v157 offset:1024
	ds_read_b128 v[164:167], v157 offset:2048
	ds_read_b128 v[168:171], v157 offset:3072
	ds_read_b128 v[180:183], v158
	ds_read_b128 v[184:187], v158 offset:1024
	ds_read_b128 v[188:191], v158 offset:2048
	ds_read_b128 v[192:195], v158 offset:3072
	s_add_u32 s60, s12, 0x100
	s_addc_u32 s61, s13, 0
	s_cmp_eq_u32 s34, 40
	s_cselect_b32 s65, s1, s61
	s_cselect_b32 s64, s0, s60
	s_cselect_b32 s63, s59, s7
	s_cselect_b32 s62, s58, s6
	s_add_i32 m0, s5, 0xc000
	ds_read_b128 v[196:199], v159
	ds_read_b128 v[200:203], v159 offset:1024
	ds_read_b128 v[204:207], v159 offset:2048
	ds_read_b128 v[208:211], v159 offset:3072
	ds_read_b128 v[212:215], v159 offset:4096
	ds_read_b128 v[216:219], v159 offset:5120
	ds_read_b128 v[220:223], v159 offset:6144
	ds_read_b128 v[224:227], v159 offset:7168
	global_load_lds_dwordx4 v136, s[12:13]
	s_add_i32 m0, s5, 0xe000
	s_nop 0
	global_load_lds_dwordx4 v138, s[12:13]
	s_waitcnt vmcnt(8)
	s_waitcnt lgkmcnt(0)
	s_barrier
	s_setprio 1
	s_waitcnt lgkmcnt(0)
	v_mfma_f32_16x16x32_bf16 v[124:127], v[144:147], v[196:199], v[124:127]
	v_mfma_f32_16x16x32_bf16 v[120:123], v[164:167], v[196:199], v[120:123]
	v_mfma_f32_16x16x32_bf16 v[108:111], v[144:147], v[204:207], v[108:111]
	v_mfma_f32_16x16x32_bf16 v[104:107], v[164:167], v[204:207], v[104:107]
	v_mfma_f32_16x16x32_bf16 v[92:95], v[144:147], v[212:215], v[92:95]
	v_mfma_f32_16x16x32_bf16 v[88:91], v[164:167], v[212:215], v[88:91]
	v_mfma_f32_16x16x32_bf16 v[76:79], v[144:147], v[220:223], v[76:79]
	v_mfma_f32_16x16x32_bf16 v[72:75], v[164:167], v[220:223], v[72:75]
	v_mfma_f32_16x16x32_bf16 v[124:127], v[148:151], v[200:203], v[124:127]
	v_mfma_f32_16x16x32_bf16 v[120:123], v[168:171], v[200:203], v[120:123]
	v_mfma_f32_16x16x32_bf16 v[108:111], v[148:151], v[208:211], v[108:111]
	v_mfma_f32_16x16x32_bf16 v[104:107], v[168:171], v[208:211], v[104:107]
	v_mfma_f32_16x16x32_bf16 v[92:95], v[148:151], v[216:219], v[92:95]
	v_mfma_f32_16x16x32_bf16 v[88:91], v[168:171], v[216:219], v[88:91]
	v_mfma_f32_16x16x32_bf16 v[76:79], v[148:151], v[224:227], v[76:79]
	v_mfma_f32_16x16x32_bf16 v[72:75], v[168:171], v[224:227], v[72:75]
	s_setprio 0
	s_setprio 1
	v_mfma_f32_16x16x32_bf16 v[116:119], v[180:183], v[196:199], v[116:119]
	v_mfma_f32_16x16x32_bf16 v[112:115], v[188:191], v[196:199], v[112:115]
	v_mfma_f32_16x16x32_bf16 v[100:103], v[180:183], v[204:207], v[100:103]
	v_mfma_f32_16x16x32_bf16 v[96:99], v[188:191], v[204:207], v[96:99]
	v_mfma_f32_16x16x32_bf16 v[84:87], v[180:183], v[212:215], v[84:87]
	v_mfma_f32_16x16x32_bf16 v[80:83], v[188:191], v[212:215], v[80:83]
	v_mfma_f32_16x16x32_bf16 v[68:71], v[180:183], v[220:223], v[68:71]
	v_mfma_f32_16x16x32_bf16 v[64:67], v[188:191], v[220:223], v[64:67]
	v_mfma_f32_16x16x32_bf16 v[116:119], v[184:187], v[200:203], v[116:119]
	v_mfma_f32_16x16x32_bf16 v[112:115], v[192:195], v[200:203], v[112:115]
	v_mfma_f32_16x16x32_bf16 v[100:103], v[184:187], v[208:211], v[100:103]
	v_mfma_f32_16x16x32_bf16 v[96:99], v[192:195], v[208:211], v[96:99]
	v_mfma_f32_16x16x32_bf16 v[84:87], v[184:187], v[216:219], v[84:87]
	v_mfma_f32_16x16x32_bf16 v[80:83], v[192:195], v[216:219], v[80:83]
	v_mfma_f32_16x16x32_bf16 v[68:71], v[184:187], v[224:227], v[68:71]
	v_mfma_f32_16x16x32_bf16 v[64:67], v[192:195], v[224:227], v[64:67]
	s_setprio 0
	s_barrier
	s_add_i32 s12, s27, s4
	s_mov_b32 m0, s12
	ds_read_b128 v[196:199], v159 offset:16384
	ds_read_b128 v[200:203], v159 offset:17408
	ds_read_b128 v[204:207], v159 offset:18432
	ds_read_b128 v[208:211], v159 offset:19456
	ds_read_b128 v[212:215], v159 offset:20480
	ds_read_b128 v[216:219], v159 offset:21504
	ds_read_b128 v[220:223], v159 offset:22528
	ds_read_b128 v[224:227], v159 offset:23552
	global_load_lds_dwordx4 v130, s[62:63]
	s_add_i32 m0, s12, 0x2000
	s_add_u32 s12, s62, 0xb0000
	s_addc_u32 s13, s63, 0
	s_add_i32 s35, s28, s4
	global_load_lds_dwordx4 v134, s[62:63]
	s_mov_b32 m0, s35
	s_nop 0
	global_load_lds_dwordx4 v130, s[12:13]
	s_add_i32 m0, s35, 0x2000
	s_nop 0
	global_load_lds_dwordx4 v134, s[12:13]
	s_mov_b32 m0, s5
	s_nop 0
	global_load_lds_dwordx4 v128, s[64:65]
	s_mov_b32 m0, s16
	s_nop 0
	global_load_lds_dwordx4 v132, s[64:65]
	s_waitcnt vmcnt(8)
	s_waitcnt lgkmcnt(0)
	s_barrier
	s_setprio 1
	s_waitcnt lgkmcnt(0)
	v_mfma_f32_16x16x32_bf16 v[60:63], v[144:147], v[196:199], v[60:63]
	v_mfma_f32_16x16x32_bf16 v[56:59], v[164:167], v[196:199], v[56:59]
	v_mfma_f32_16x16x32_bf16 v[44:47], v[144:147], v[204:207], v[44:47]
	v_mfma_f32_16x16x32_bf16 v[40:43], v[164:167], v[204:207], v[40:43]
	v_mfma_f32_16x16x32_bf16 v[28:31], v[144:147], v[212:215], v[28:31]
	v_mfma_f32_16x16x32_bf16 v[24:27], v[164:167], v[212:215], v[24:27]
	v_mfma_f32_16x16x32_bf16 v[12:15], v[144:147], v[220:223], v[12:15]
	v_mfma_f32_16x16x32_bf16 v[8:11], v[164:167], v[220:223], v[8:11]
	v_mfma_f32_16x16x32_bf16 v[60:63], v[148:151], v[200:203], v[60:63]
	v_mfma_f32_16x16x32_bf16 v[56:59], v[168:171], v[200:203], v[56:59]
	v_mfma_f32_16x16x32_bf16 v[44:47], v[148:151], v[208:211], v[44:47]
	v_mfma_f32_16x16x32_bf16 v[40:43], v[168:171], v[208:211], v[40:43]
	v_mfma_f32_16x16x32_bf16 v[28:31], v[148:151], v[216:219], v[28:31]
	v_mfma_f32_16x16x32_bf16 v[24:27], v[168:171], v[216:219], v[24:27]
	v_mfma_f32_16x16x32_bf16 v[12:15], v[148:151], v[224:227], v[12:15]
	v_mfma_f32_16x16x32_bf16 v[8:11], v[168:171], v[224:227], v[8:11]
	s_setprio 0
	s_setprio 1
	v_mfma_f32_16x16x32_bf16 v[52:55], v[180:183], v[196:199], v[52:55]
	v_mfma_f32_16x16x32_bf16 v[48:51], v[188:191], v[196:199], v[48:51]
	v_mfma_f32_16x16x32_bf16 v[36:39], v[180:183], v[204:207], v[36:39]
	v_mfma_f32_16x16x32_bf16 v[32:35], v[188:191], v[204:207], v[32:35]
	v_mfma_f32_16x16x32_bf16 v[20:23], v[180:183], v[212:215], v[20:23]
	v_mfma_f32_16x16x32_bf16 v[16:19], v[188:191], v[212:215], v[16:19]
	v_mfma_f32_16x16x32_bf16 v[4:7], v[180:183], v[220:223], v[4:7]
	v_mfma_f32_16x16x32_bf16 v[0:3], v[188:191], v[220:223], v[0:3]
	v_mfma_f32_16x16x32_bf16 v[52:55], v[184:187], v[200:203], v[52:55]
	v_mfma_f32_16x16x32_bf16 v[48:51], v[192:195], v[200:203], v[48:51]
	v_mfma_f32_16x16x32_bf16 v[36:39], v[184:187], v[208:211], v[36:39]
	v_mfma_f32_16x16x32_bf16 v[32:35], v[192:195], v[208:211], v[32:35]
	v_mfma_f32_16x16x32_bf16 v[20:23], v[184:187], v[216:219], v[20:23]
	v_mfma_f32_16x16x32_bf16 v[16:19], v[192:195], v[216:219], v[16:19]
	v_mfma_f32_16x16x32_bf16 v[4:7], v[184:187], v[224:227], v[4:7]
	v_mfma_f32_16x16x32_bf16 v[0:3], v[192:195], v[224:227], v[0:3]
	s_setprio 0
	s_barrier
; #define PG8_STAGE(bufoff, gbase, voff) do { _Pragma("unroll") for (int _i = 0; _i < 2; ++_i) \
;         __builtin_amdgcn_global_load_lds((const unsigned*)((const char*)(gbase) + (voff)[_i]), (LAS unsigned*)(lds + (bufoff) + ldsw + _i * 8192), 16, 0, 0); } while (0)
; #define PG8_LDA(dst, b, h) do { _Pragma("unroll") for (int m = 0; m < 4; ++m) _Pragma("unroll") for (int k = 0; k < 2; ++k) dst[m][k] = *(const LAS bf16x8*)(lds + PG8_SA(b, h) + aoff + m * 2048 + k * 1024); } while (0)
; #define PG8_LDB(dst, b, h) do { _Pragma("unroll") for (int n = 0; n < 2; ++n) _Pragma("unroll") for (int k = 0; k < 2; ++k) dst[n][k] = *(const LAS bf16x8*)(lds + PG8_SB(b, h) + boff + n * 2048 + k * 1024); } while (0)
; #define PG8_MMA(ai, bj, At, Bt) do { __builtin_amdgcn_s_setprio(1); _Pragma("unroll") for (int m = 0; m < 4; ++m) _Pragma("unroll") for (int n = 0; n < 2; ++n) _Pragma("unroll") for (int k = 0; k < 2; ++k) \
;         acc[ai][bj][m][n] = __builtin_amdgcn_mfma_f32_16x16x32_bf16(Bt[n][k], At[m][k], acc[ai][bj][m][n], 0, 0, 0); __builtin_amdgcn_s_setprio(0); } while (0)
; #define PG8_WAIT_V(n) asm volatile("s_waitcnt vmcnt(" #n ")" ::: "memory")
; #define PG8_WAIT_L(n) asm volatile("s_waitcnt lgkmcnt(" #n ")" ::: "memory")
; #define PG8_BAR __builtin_amdgcn_s_barrier()
; #define PG8_SCHED __builtin_amdgcn_sched_barrier(0)
; template <class Epi>
; __device__ __forceinline__ void gemm_phase(LAS unsigned char* lds, const Gemm g, const StaticOrder& S, const Epi& E) {
;     ...
;             PG8_LDB(B0, 1, 0); PG8_LDB(B1, 1, 1); PG8_SCHED; PG8_LDA(At, 1, 0); PG8_STAGE(PG8_SA(0, 1), a2 + hsA, voffA);
;             PG8_WAIT_V(8); PG8_WAIT_L(0); PG8_BAR; PG8_MMA(0, 0, At, B0); PG8_MMA(0, 1, At, B1); PG8_BAR; PG8_SCHED;
;             PG8_LDA(At, 1, 1); PG8_STAGE(PG8_SB(1, 0), b3, voffB); PG8_STAGE(PG8_SB(1, 1), b3 + hsB, voffB); PG8_STAGE(PG8_SA(1, 0), a3, voffA);
;             PG8_WAIT_V(8); PG8_WAIT_L(0); PG8_BAR; PG8_MMA(1, 0, At, B0); PG8_MMA(1, 1, At, B1); PG8_BAR; PG8_SCHED;
;         }
	s_add_i32 s35, 0, 0x18000
	v_add_u32_e32 v163, s35, v155
	s_add_i32 s36, 0, 0x1c000
	ds_read_b128 v[144:147], v163
	ds_read_b128 v[148:151], v163 offset:1024
	ds_read_b128 v[164:167], v163 offset:2048
	ds_read_b128 v[168:171], v163 offset:3072
	v_add_u32_e32 v163, s36, v155
	ds_read_b128 v[180:183], v163
	ds_read_b128 v[184:187], v163 offset:1024
	ds_read_b128 v[188:191], v163 offset:2048
	ds_read_b128 v[192:195], v163 offset:3072
	s_add_u32 s12, s64, 0xb0000
	s_addc_u32 s13, s65, 0
	s_mov_b32 m0, s17
	ds_read_b128 v[196:199], v159 offset:32768
	ds_read_b128 v[200:203], v159 offset:33792
	ds_read_b128 v[204:207], v159 offset:34816
	ds_read_b128 v[208:211], v159 offset:35840
	ds_read_b128 v[212:215], v159 offset:36864
	ds_read_b128 v[216:219], v159 offset:37888
	ds_read_b128 v[220:223], v159 offset:38912
	ds_read_b128 v[224:227], v159 offset:39936
	global_load_lds_dwordx4 v128, s[12:13]
	s_mov_b32 m0, s18
	s_nop 0
	global_load_lds_dwordx4 v132, s[12:13]
	s_waitcnt vmcnt(8)
	s_waitcnt lgkmcnt(0)
	s_barrier
	s_setprio 1
	s_waitcnt lgkmcnt(0)
	v_mfma_f32_16x16x32_bf16 v[124:127], v[144:147], v[196:199], v[124:127]
	v_mfma_f32_16x16x32_bf16 v[120:123], v[164:167], v[196:199], v[120:123]
	v_mfma_f32_16x16x32_bf16 v[108:111], v[144:147], v[204:207], v[108:111]
	v_mfma_f32_16x16x32_bf16 v[104:107], v[164:167], v[204:207], v[104:107]
	v_mfma_f32_16x16x32_bf16 v[92:95], v[144:147], v[212:215], v[92:95]
	v_mfma_f32_16x16x32_bf16 v[88:91], v[164:167], v[212:215], v[88:91]
	v_mfma_f32_16x16x32_bf16 v[76:79], v[144:147], v[220:223], v[76:79]
	v_mfma_f32_16x16x32_bf16 v[72:75], v[164:167], v[220:223], v[72:75]
	v_mfma_f32_16x16x32_bf16 v[124:127], v[148:151], v[200:203], v[124:127]
	v_mfma_f32_16x16x32_bf16 v[120:123], v[168:171], v[200:203], v[120:123]
	v_mfma_f32_16x16x32_bf16 v[108:111], v[148:151], v[208:211], v[108:111]
	v_mfma_f32_16x16x32_bf16 v[104:107], v[168:171], v[208:211], v[104:107]
	v_mfma_f32_16x16x32_bf16 v[92:95], v[148:151], v[216:219], v[92:95]
	v_mfma_f32_16x16x32_bf16 v[88:91], v[168:171], v[216:219], v[88:91]
	v_mfma_f32_16x16x32_bf16 v[76:79], v[148:151], v[224:227], v[76:79]
	v_mfma_f32_16x16x32_bf16 v[72:75], v[168:171], v[224:227], v[72:75]
	s_setprio 0
	s_setprio 1
	v_mfma_f32_16x16x32_bf16 v[116:119], v[180:183], v[196:199], v[116:119]
	v_mfma_f32_16x16x32_bf16 v[112:115], v[188:191], v[196:199], v[112:115]
	v_mfma_f32_16x16x32_bf16 v[100:103], v[180:183], v[204:207], v[100:103]
	v_mfma_f32_16x16x32_bf16 v[96:99], v[188:191], v[204:207], v[96:99]
	v_mfma_f32_16x16x32_bf16 v[84:87], v[180:183], v[212:215], v[84:87]
	v_mfma_f32_16x16x32_bf16 v[80:83], v[188:191], v[212:215], v[80:83]
	v_mfma_f32_16x16x32_bf16 v[68:71], v[180:183], v[220:223], v[68:71]
	v_mfma_f32_16x16x32_bf16 v[64:67], v[188:191], v[220:223], v[64:67]
	v_mfma_f32_16x16x32_bf16 v[116:119], v[184:187], v[200:203], v[116:119]
	v_mfma_f32_16x16x32_bf16 v[112:115], v[192:195], v[200:203], v[112:115]
	v_mfma_f32_16x16x32_bf16 v[100:103], v[184:187], v[208:211], v[100:103]
	v_mfma_f32_16x16x32_bf16 v[96:99], v[192:195], v[208:211], v[96:99]
	v_mfma_f32_16x16x32_bf16 v[84:87], v[184:187], v[216:219], v[84:87]
	v_mfma_f32_16x16x32_bf16 v[80:83], v[192:195], v[216:219], v[80:83]
	v_mfma_f32_16x16x32_bf16 v[68:71], v[184:187], v[224:227], v[68:71]
	v_mfma_f32_16x16x32_bf16 v[64:67], v[192:195], v[224:227], v[64:67]
	s_setprio 0
	s_barrier
	s_add_u32 s98, s62, 0x80
	s_addc_u32 s99, s63, 0
	s_add_u32 s100, s64, 0x80
	s_addc_u32 s101, s65, 0
	s_add_i32 s12, s35, s4
	s_mov_b32 m0, s12
	ds_read_b128 v[196:199], v159 offset:49152
	ds_read_b128 v[200:203], v159 offset:50176
	ds_read_b128 v[204:207], v159 offset:51200
	ds_read_b128 v[208:211], v159 offset:52224
	ds_read_b128 v[212:215], v159 offset:53248
	ds_read_b128 v[216:219], v159 offset:54272
	ds_read_b128 v[220:223], v159 offset:55296
	ds_read_b128 v[224:227], v159 offset:56320
	global_load_lds_dwordx4 v130, s[98:99]
	s_add_i32 m0, s12, 0x2000
	s_add_u32 s12, s62, 0xb0080
	s_addc_u32 s13, s63, 0
	s_add_i32 s35, s36, s4
	global_load_lds_dwordx4 v134, s[98:99]
	s_mov_b32 m0, s35
	s_nop 0
	global_load_lds_dwordx4 v130, s[12:13]
	s_add_i32 m0, s35, 0x2000
	s_nop 0
	global_load_lds_dwordx4 v134, s[12:13]
	s_mov_b32 m0, s22
	s_nop 0
	global_load_lds_dwordx4 v128, s[100:101]
	s_mov_b32 m0, s23
	s_nop 0
	global_load_lds_dwordx4 v132, s[100:101]
	s_waitcnt vmcnt(8)
	s_waitcnt lgkmcnt(0)
	s_barrier
	s_setprio 1
	s_waitcnt lgkmcnt(0)
	v_mfma_f32_16x16x32_bf16 v[60:63], v[144:147], v[196:199], v[60:63]
	v_mfma_f32_16x16x32_bf16 v[56:59], v[164:167], v[196:199], v[56:59]
	v_mfma_f32_16x16x32_bf16 v[44:47], v[144:147], v[204:207], v[44:47]
	v_mfma_f32_16x16x32_bf16 v[40:43], v[164:167], v[204:207], v[40:43]
	v_mfma_f32_16x16x32_bf16 v[28:31], v[144:147], v[212:215], v[28:31]
	v_mfma_f32_16x16x32_bf16 v[24:27], v[164:167], v[212:215], v[24:27]
	v_mfma_f32_16x16x32_bf16 v[12:15], v[144:147], v[220:223], v[12:15]
	v_mfma_f32_16x16x32_bf16 v[8:11], v[164:167], v[220:223], v[8:11]
	v_mfma_f32_16x16x32_bf16 v[60:63], v[148:151], v[200:203], v[60:63]
	v_mfma_f32_16x16x32_bf16 v[56:59], v[168:171], v[200:203], v[56:59]
	v_mfma_f32_16x16x32_bf16 v[44:47], v[148:151], v[208:211], v[44:47]
	v_mfma_f32_16x16x32_bf16 v[40:43], v[168:171], v[208:211], v[40:43]
	v_mfma_f32_16x16x32_bf16 v[28:31], v[148:151], v[216:219], v[28:31]
	v_mfma_f32_16x16x32_bf16 v[24:27], v[168:171], v[216:219], v[24:27]
	v_mfma_f32_16x16x32_bf16 v[12:15], v[148:151], v[224:227], v[12:15]
	v_mfma_f32_16x16x32_bf16 v[8:11], v[168:171], v[224:227], v[8:11]
	s_setprio 0
	s_setprio 1
	v_mfma_f32_16x16x32_bf16 v[52:55], v[180:183], v[196:199], v[52:55]
	v_mfma_f32_16x16x32_bf16 v[48:51], v[188:191], v[196:199], v[48:51]
	v_mfma_f32_16x16x32_bf16 v[36:39], v[180:183], v[204:207], v[36:39]
	v_mfma_f32_16x16x32_bf16 v[32:35], v[188:191], v[204:207], v[32:35]
	v_mfma_f32_16x16x32_bf16 v[20:23], v[180:183], v[212:215], v[20:23]
	v_mfma_f32_16x16x32_bf16 v[16:19], v[188:191], v[212:215], v[16:19]
	v_mfma_f32_16x16x32_bf16 v[4:7], v[180:183], v[220:223], v[4:7]
	v_mfma_f32_16x16x32_bf16 v[0:3], v[188:191], v[220:223], v[0:3]
	v_mfma_f32_16x16x32_bf16 v[52:55], v[184:187], v[200:203], v[52:55]
	v_mfma_f32_16x16x32_bf16 v[48:51], v[192:195], v[200:203], v[48:51]
	v_mfma_f32_16x16x32_bf16 v[36:39], v[184:187], v[208:211], v[36:39]
	v_mfma_f32_16x16x32_bf16 v[32:35], v[192:195], v[208:211], v[32:35]
	v_mfma_f32_16x16x32_bf16 v[20:23], v[184:187], v[216:219], v[20:23]
	v_mfma_f32_16x16x32_bf16 v[16:19], v[192:195], v[216:219], v[16:19]
	v_mfma_f32_16x16x32_bf16 v[4:7], v[184:187], v[224:227], v[4:7]
	v_mfma_f32_16x16x32_bf16 v[0:3], v[192:195], v[224:227], v[0:3]
	s_add_i32 s34, s34, 2
	s_add_u32 s6, s6, 0x100
	s_addc_u32 s7, s7, 0
	s_cmp_gt_u32 s34, 41
	s_mov_b64 s[12:13], s[60:61]
	s_setprio 0
	s_barrier
	s_cbranch_scc0 .LBB0_296
	s_and_b64 vcc, exec, s[42:43]
	s_cbranch_vccz .LBB0_299
	s_barrier

; #define PG8_STAGE(bufoff, gbase, voff) do { _Pragma("unroll") for (int _i = 0; _i < 2; ++_i) \
;         __builtin_amdgcn_global_load_lds((const unsigned*)((const char*)(gbase) + (voff)[_i]), (LAS unsigned*)(lds + (bufoff) + ldsw + _i * 8192), 16, 0, 0); } while (0)
; #define PG8_LDA(dst, b, h) do { _Pragma("unroll") for (int m = 0; m < 4; ++m) _Pragma("unroll") for (int k = 0; k < 2; ++k) dst[m][k] = *(const LAS bf16x8*)(lds + PG8_SA(b, h) + aoff + m * 2048 + k * 1024); } while (0)
; #define PG8_LDB(dst, b, h) do { _Pragma("unroll") for (int n = 0; n < 2; ++n) _Pragma("unroll") for (int k = 0; k < 2; ++k) dst[n][k] = *(const LAS bf16x8*)(lds + PG8_SB(b, h) + boff + n * 2048 + k * 1024); } while (0)
; #define PG8_MMA(ai, bj, At, Bt) do { __builtin_amdgcn_s_setprio(1); _Pragma("unroll") for (int m = 0; m < 4; ++m) _Pragma("unroll") for (int n = 0; n < 2; ++n) _Pragma("unroll") for (int k = 0; k < 2; ++k) \
;         acc[ai][bj][m][n] = __builtin_amdgcn_mfma_f32_16x16x32_bf16(Bt[n][k], At[m][k], acc[ai][bj][m][n], 0, 0, 0); __builtin_amdgcn_s_setprio(0); } while (0)
; #define PG8_WAIT_V(n) asm volatile("s_waitcnt vmcnt(" #n ")" ::: "memory")
; #define PG8_WAIT_L(n) asm volatile("s_waitcnt lgkmcnt(" #n ")" ::: "memory")
; #define PG8_BAR __builtin_amdgcn_s_barrier()
; #define PG8_SCHED __builtin_amdgcn_sched_barrier(0)
; template <class Epi>
; __device__ __forceinline__ void gemm_phase(LAS unsigned char* lds, const Gemm g, const StaticOrder& S, const Epi& E) {
;     ...
;             PG8_LDB(B0, 0, 0); PG8_LDB(B1, 0, 1); PG8_SCHED; PG8_LDA(At, 0, 0); PG8_STAGE(PG8_SA(1, 1), a1 + hsA, voffA);
;             PG8_WAIT_V(8); PG8_WAIT_L(0); PG8_BAR; PG8_MMA(0, 0, At, B0); PG8_MMA(0, 1, At, B1); PG8_BAR; PG8_SCHED;
;             PG8_LDA(At, 0, 1); PG8_STAGE(PG8_SB(0, 0), b2, voffB); PG8_STAGE(PG8_SB(0, 1), b2 + hsB, voffB); PG8_STAGE(PG8_SA(0, 0), a2, voffA);
;             PG8_WAIT_V(8); PG8_WAIT_L(0); PG8_BAR; PG8_MMA(1, 0, At, B0); PG8_MMA(1, 1, At, B1); PG8_BAR; PG8_SCHED;
.LBB0_414:
	ds_read_b128 v[152:155], v167
	ds_read_b128 v[156:159], v167 offset:1024
	ds_read_b128 v[162:165], v167 offset:2048
	ds_read_b128 v[180:183], v167 offset:3072
	ds_read_b128 v[184:187], v168
	ds_read_b128 v[188:191], v168 offset:1024
	ds_read_b128 v[192:195], v168 offset:2048
	ds_read_b128 v[196:199], v168 offset:3072
	s_add_u32 s12, s10, 0xfffc0080
	s_addc_u32 s13, s11, -1
	s_cmp_eq_u32 s17, 12
	s_cselect_b32 s87, s0, s13
	s_cselect_b32 s86, s2, s12
	s_cselect_b32 s13, s3, s15
	s_cselect_b32 s12, s6, s7
	s_add_i32 m0, s5, 0xc000
	ds_read_b128 v[200:203], v169
	ds_read_b128 v[204:207], v169 offset:1024
	ds_read_b128 v[208:211], v169 offset:2048
	ds_read_b128 v[212:215], v169 offset:3072
	ds_read_b128 v[216:219], v169 offset:4096
	ds_read_b128 v[220:223], v169 offset:5120
	ds_read_b128 v[224:227], v169 offset:6144
	ds_read_b128 v[228:231], v169 offset:7168
	global_load_lds_dwordx4 v144, s[10:11]
	s_add_i32 m0, s5, 0xe000
	s_nop 0
	global_load_lds_dwordx4 v146, s[10:11]
	s_waitcnt vmcnt(8)
	s_waitcnt lgkmcnt(0)
	s_barrier
	s_setprio 1
	s_waitcnt lgkmcnt(0)
	v_mfma_f32_16x16x32_bf16 v[124:127], v[152:155], v[200:203], v[124:127]
	v_mfma_f32_16x16x32_bf16 v[120:123], v[162:165], v[200:203], v[120:123]
	v_mfma_f32_16x16x32_bf16 v[108:111], v[152:155], v[208:211], v[108:111]
	v_mfma_f32_16x16x32_bf16 v[104:107], v[162:165], v[208:211], v[104:107]
	v_mfma_f32_16x16x32_bf16 v[92:95], v[152:155], v[216:219], v[92:95]
	v_mfma_f32_16x16x32_bf16 v[88:91], v[162:165], v[216:219], v[88:91]
	v_mfma_f32_16x16x32_bf16 v[76:79], v[152:155], v[224:227], v[76:79]
	v_mfma_f32_16x16x32_bf16 v[72:75], v[162:165], v[224:227], v[72:75]
	v_mfma_f32_16x16x32_bf16 v[124:127], v[156:159], v[204:207], v[124:127]
	v_mfma_f32_16x16x32_bf16 v[120:123], v[180:183], v[204:207], v[120:123]
	v_mfma_f32_16x16x32_bf16 v[108:111], v[156:159], v[212:215], v[108:111]
	v_mfma_f32_16x16x32_bf16 v[104:107], v[180:183], v[212:215], v[104:107]
	v_mfma_f32_16x16x32_bf16 v[92:95], v[156:159], v[220:223], v[92:95]
	v_mfma_f32_16x16x32_bf16 v[88:91], v[180:183], v[220:223], v[88:91]
	v_mfma_f32_16x16x32_bf16 v[76:79], v[156:159], v[228:231], v[76:79]
	v_mfma_f32_16x16x32_bf16 v[72:75], v[180:183], v[228:231], v[72:75]
	s_setprio 0
	s_setprio 1
	v_mfma_f32_16x16x32_bf16 v[116:119], v[184:187], v[200:203], v[116:119]
	v_mfma_f32_16x16x32_bf16 v[112:115], v[192:195], v[200:203], v[112:115]
	v_mfma_f32_16x16x32_bf16 v[100:103], v[184:187], v[208:211], v[100:103]
	v_mfma_f32_16x16x32_bf16 v[96:99], v[192:195], v[208:211], v[96:99]
	v_mfma_f32_16x16x32_bf16 v[84:87], v[184:187], v[216:219], v[84:87]
	v_mfma_f32_16x16x32_bf16 v[80:83], v[192:195], v[216:219], v[80:83]
	v_mfma_f32_16x16x32_bf16 v[68:71], v[184:187], v[224:227], v[68:71]
	v_mfma_f32_16x16x32_bf16 v[64:67], v[192:195], v[224:227], v[64:67]
	v_mfma_f32_16x16x32_bf16 v[116:119], v[188:191], v[204:207], v[116:119]
	v_mfma_f32_16x16x32_bf16 v[112:115], v[196:199], v[204:207], v[112:115]
	v_mfma_f32_16x16x32_bf16 v[100:103], v[188:191], v[212:215], v[100:103]
	v_mfma_f32_16x16x32_bf16 v[96:99], v[196:199], v[212:215], v[96:99]
	v_mfma_f32_16x16x32_bf16 v[84:87], v[188:191], v[220:223], v[84:87]
	v_mfma_f32_16x16x32_bf16 v[80:83], v[196:199], v[220:223], v[80:83]
	v_mfma_f32_16x16x32_bf16 v[68:71], v[188:191], v[228:231], v[68:71]
	v_mfma_f32_16x16x32_bf16 v[64:67], v[196:199], v[228:231], v[64:67]
	s_setprio 0
	s_barrier
	s_add_i32 s19, s65, s4
	s_mov_b32 m0, s19
	ds_read_b128 v[200:203], v169 offset:16384
	ds_read_b128 v[204:207], v169 offset:17408
	ds_read_b128 v[208:211], v169 offset:18432
	ds_read_b128 v[212:215], v169 offset:19456
	ds_read_b128 v[216:219], v169 offset:20480
	ds_read_b128 v[220:223], v169 offset:21504
	ds_read_b128 v[224:227], v169 offset:22528
	ds_read_b128 v[228:231], v169 offset:23552
	global_load_lds_dwordx4 v130, s[12:13]
	s_add_i32 m0, s19, 0x2000
	s_add_u32 s24, s12, 0x40000
	s_addc_u32 s25, s13, 0
	s_add_i32 s19, s76, s4
	global_load_lds_dwordx4 v134, s[12:13]
	s_mov_b32 m0, s19
	s_nop 0
	global_load_lds_dwordx4 v130, s[24:25]
	s_add_i32 m0, s19, 0x2000
	s_nop 0
	global_load_lds_dwordx4 v134, s[24:25]
	s_mov_b32 m0, s5
	s_nop 0
	global_load_lds_dwordx4 v128, s[86:87]
	s_mov_b32 m0, s62
	s_nop 0
	global_load_lds_dwordx4 v132, s[86:87]
	s_waitcnt vmcnt(8)
	s_waitcnt lgkmcnt(0)
	s_barrier
	s_setprio 1
	s_waitcnt lgkmcnt(0)
	v_mfma_f32_16x16x32_bf16 v[60:63], v[152:155], v[200:203], v[60:63]
	v_mfma_f32_16x16x32_bf16 v[56:59], v[162:165], v[200:203], v[56:59]
	v_mfma_f32_16x16x32_bf16 v[44:47], v[152:155], v[208:211], v[44:47]
	v_mfma_f32_16x16x32_bf16 v[40:43], v[162:165], v[208:211], v[40:43]
	v_mfma_f32_16x16x32_bf16 v[28:31], v[152:155], v[216:219], v[28:31]
	v_mfma_f32_16x16x32_bf16 v[24:27], v[162:165], v[216:219], v[24:27]
	v_mfma_f32_16x16x32_bf16 v[12:15], v[152:155], v[224:227], v[12:15]
	v_mfma_f32_16x16x32_bf16 v[8:11], v[162:165], v[224:227], v[8:11]
	v_mfma_f32_16x16x32_bf16 v[60:63], v[156:159], v[204:207], v[60:63]
	v_mfma_f32_16x16x32_bf16 v[56:59], v[180:183], v[204:207], v[56:59]
	v_mfma_f32_16x16x32_bf16 v[44:47], v[156:159], v[212:215], v[44:47]
	v_mfma_f32_16x16x32_bf16 v[40:43], v[180:183], v[212:215], v[40:43]
	v_mfma_f32_16x16x32_bf16 v[28:31], v[156:159], v[220:223], v[28:31]
	v_mfma_f32_16x16x32_bf16 v[24:27], v[180:183], v[220:223], v[24:27]
	v_mfma_f32_16x16x32_bf16 v[12:15], v[156:159], v[228:231], v[12:15]
	v_mfma_f32_16x16x32_bf16 v[8:11], v[180:183], v[228:231], v[8:11]
	s_setprio 0
	s_setprio 1
	v_mfma_f32_16x16x32_bf16 v[52:55], v[184:187], v[200:203], v[52:55]
	v_mfma_f32_16x16x32_bf16 v[48:51], v[192:195], v[200:203], v[48:51]
	v_mfma_f32_16x16x32_bf16 v[36:39], v[184:187], v[208:211], v[36:39]
	v_mfma_f32_16x16x32_bf16 v[32:35], v[192:195], v[208:211], v[32:35]
	v_mfma_f32_16x16x32_bf16 v[20:23], v[184:187], v[216:219], v[20:23]
	v_mfma_f32_16x16x32_bf16 v[16:19], v[192:195], v[216:219], v[16:19]
	v_mfma_f32_16x16x32_bf16 v[4:7], v[184:187], v[224:227], v[4:7]
	v_mfma_f32_16x16x32_bf16 v[0:3], v[192:195], v[224:227], v[0:3]
	v_mfma_f32_16x16x32_bf16 v[52:55], v[188:191], v[204:207], v[52:55]
	v_mfma_f32_16x16x32_bf16 v[48:51], v[196:199], v[204:207], v[48:51]
	v_mfma_f32_16x16x32_bf16 v[36:39], v[188:191], v[212:215], v[36:39]
	v_mfma_f32_16x16x32_bf16 v[32:35], v[196:199], v[212:215], v[32:35]
	v_mfma_f32_16x16x32_bf16 v[20:23], v[188:191], v[220:223], v[20:23]
	v_mfma_f32_16x16x32_bf16 v[16:19], v[196:199], v[220:223], v[16:19]
	v_mfma_f32_16x16x32_bf16 v[4:7], v[188:191], v[228:231], v[4:7]
	v_mfma_f32_16x16x32_bf16 v[0:3], v[196:199], v[228:231], v[0:3]
	s_setprio 0
	s_barrier
; #define PG8_STAGE(bufoff, gbase, voff) do { _Pragma("unroll") for (int _i = 0; _i < 2; ++_i) \
;         __builtin_amdgcn_global_load_lds((const unsigned*)((const char*)(gbase) + (voff)[_i]), (LAS unsigned*)(lds + (bufoff) + ldsw + _i * 8192), 16, 0, 0); } while (0)
; #define PG8_LDA(dst, b, h) do { _Pragma("unroll") for (int m = 0; m < 4; ++m) _Pragma("unroll") for (int k = 0; k < 2; ++k) dst[m][k] = *(const LAS bf16x8*)(lds + PG8_SA(b, h) + aoff + m * 2048 + k * 1024); } while (0)
; #define PG8_LDB(dst, b, h) do { _Pragma("unroll") for (int n = 0; n < 2; ++n) _Pragma("unroll") for (int k = 0; k < 2; ++k) dst[n][k] = *(const LAS bf16x8*)(lds + PG8_SB(b, h) + boff + n * 2048 + k * 1024); } while (0)
; #define PG8_MMA(ai, bj, At, Bt) do { __builtin_amdgcn_s_setprio(1); _Pragma("unroll") for (int m = 0; m < 4; ++m) _Pragma("unroll") for (int n = 0; n < 2; ++n) _Pragma("unroll") for (int k = 0; k < 2; ++k) \
;         acc[ai][bj][m][n] = __builtin_amdgcn_mfma_f32_16x16x32_bf16(Bt[n][k], At[m][k], acc[ai][bj][m][n], 0, 0, 0); __builtin_amdgcn_s_setprio(0); } while (0)
; #define PG8_WAIT_V(n) asm volatile("s_waitcnt vmcnt(" #n ")" ::: "memory")
; #define PG8_WAIT_L(n) asm volatile("s_waitcnt lgkmcnt(" #n ")" ::: "memory")
; #define PG8_BAR __builtin_amdgcn_s_barrier()
; #define PG8_SCHED __builtin_amdgcn_sched_barrier(0)
; template <class Epi>
; __device__ __forceinline__ void gemm_phase(LAS unsigned char* lds, const Gemm g, const StaticOrder& S, const Epi& E) {
;     ...
;             PG8_LDB(B0, 1, 0); PG8_LDB(B1, 1, 1); PG8_SCHED; PG8_LDA(At, 1, 0); PG8_STAGE(PG8_SA(0, 1), a2 + hsA, voffA);
;             PG8_WAIT_V(8); PG8_WAIT_L(0); PG8_BAR; PG8_MMA(0, 0, At, B0); PG8_MMA(0, 1, At, B1); PG8_BAR; PG8_SCHED;
;             PG8_LDA(At, 1, 1); PG8_STAGE(PG8_SB(1, 0), b3, voffB); PG8_STAGE(PG8_SB(1, 1), b3 + hsB, voffB); PG8_STAGE(PG8_SA(1, 0), a3, voffA);
;             PG8_WAIT_V(8); PG8_WAIT_L(0); PG8_BAR; PG8_MMA(1, 0, At, B0); PG8_MMA(1, 1, At, B1); PG8_BAR; PG8_SCHED;
;         }
	s_add_i32 s19, 0, 0x18000
	v_add_u32_e32 v136, s19, v166
	s_add_i32 s22, 0, 0x1c000
	ds_read_b128 v[152:155], v136
	ds_read_b128 v[156:159], v136 offset:1024
	ds_read_b128 v[162:165], v136 offset:2048
	ds_read_b128 v[180:183], v136 offset:3072
	v_add_u32_e32 v136, s22, v166
	ds_read_b128 v[184:187], v136
	ds_read_b128 v[188:191], v136 offset:1024
	ds_read_b128 v[192:195], v136 offset:2048
	ds_read_b128 v[196:199], v136 offset:3072
	s_add_u32 s24, s86, 0x40000
	s_addc_u32 s25, s87, 0
	s_mov_b32 m0, s63
	ds_read_b128 v[200:203], v169 offset:32768
	ds_read_b128 v[204:207], v169 offset:33792
	ds_read_b128 v[208:211], v169 offset:34816
	ds_read_b128 v[212:215], v169 offset:35840
	ds_read_b128 v[216:219], v169 offset:36864
	ds_read_b128 v[220:223], v169 offset:37888
	ds_read_b128 v[224:227], v169 offset:38912
	ds_read_b128 v[228:231], v169 offset:39936
	global_load_lds_dwordx4 v128, s[24:25]
	s_mov_b32 m0, s74
	s_nop 0
	global_load_lds_dwordx4 v132, s[24:25]
	s_waitcnt vmcnt(8)
	s_waitcnt lgkmcnt(0)
	s_barrier
	s_setprio 1
	s_waitcnt lgkmcnt(0)
	v_mfma_f32_16x16x32_bf16 v[124:127], v[152:155], v[200:203], v[124:127]
	v_mfma_f32_16x16x32_bf16 v[120:123], v[162:165], v[200:203], v[120:123]
	v_mfma_f32_16x16x32_bf16 v[108:111], v[152:155], v[208:211], v[108:111]
	v_mfma_f32_16x16x32_bf16 v[104:107], v[162:165], v[208:211], v[104:107]
	v_mfma_f32_16x16x32_bf16 v[92:95], v[152:155], v[216:219], v[92:95]
	v_mfma_f32_16x16x32_bf16 v[88:91], v[162:165], v[216:219], v[88:91]
	v_mfma_f32_16x16x32_bf16 v[76:79], v[152:155], v[224:227], v[76:79]
	v_mfma_f32_16x16x32_bf16 v[72:75], v[162:165], v[224:227], v[72:75]
	v_mfma_f32_16x16x32_bf16 v[124:127], v[156:159], v[204:207], v[124:127]
	v_mfma_f32_16x16x32_bf16 v[120:123], v[180:183], v[204:207], v[120:123]
	v_mfma_f32_16x16x32_bf16 v[108:111], v[156:159], v[212:215], v[108:111]
	v_mfma_f32_16x16x32_bf16 v[104:107], v[180:183], v[212:215], v[104:107]
	v_mfma_f32_16x16x32_bf16 v[92:95], v[156:159], v[220:223], v[92:95]
	v_mfma_f32_16x16x32_bf16 v[88:91], v[180:183], v[220:223], v[88:91]
	v_mfma_f32_16x16x32_bf16 v[76:79], v[156:159], v[228:231], v[76:79]
	v_mfma_f32_16x16x32_bf16 v[72:75], v[180:183], v[228:231], v[72:75]
	s_setprio 0
	s_setprio 1
	v_mfma_f32_16x16x32_bf16 v[116:119], v[184:187], v[200:203], v[116:119]
	v_mfma_f32_16x16x32_bf16 v[112:115], v[192:195], v[200:203], v[112:115]
	v_mfma_f32_16x16x32_bf16 v[100:103], v[184:187], v[208:211], v[100:103]
	v_mfma_f32_16x16x32_bf16 v[96:99], v[192:195], v[208:211], v[96:99]
	v_mfma_f32_16x16x32_bf16 v[84:87], v[184:187], v[216:219], v[84:87]
	v_mfma_f32_16x16x32_bf16 v[80:83], v[192:195], v[216:219], v[80:83]
	v_mfma_f32_16x16x32_bf16 v[68:71], v[184:187], v[224:227], v[68:71]
	v_mfma_f32_16x16x32_bf16 v[64:67], v[192:195], v[224:227], v[64:67]
	v_mfma_f32_16x16x32_bf16 v[116:119], v[188:191], v[204:207], v[116:119]
	v_mfma_f32_16x16x32_bf16 v[112:115], v[196:199], v[204:207], v[112:115]
	v_mfma_f32_16x16x32_bf16 v[100:103], v[188:191], v[212:215], v[100:103]
	v_mfma_f32_16x16x32_bf16 v[96:99], v[196:199], v[212:215], v[96:99]
	v_mfma_f32_16x16x32_bf16 v[84:87], v[188:191], v[220:223], v[84:87]
	v_mfma_f32_16x16x32_bf16 v[80:83], v[196:199], v[220:223], v[80:83]
	v_mfma_f32_16x16x32_bf16 v[68:71], v[188:191], v[228:231], v[68:71]
	v_mfma_f32_16x16x32_bf16 v[64:67], v[196:199], v[228:231], v[64:67]
	s_setprio 0
	s_barrier
	s_add_u32 s98, s12, 0x80
	s_addc_u32 s99, s13, 0
	s_add_u32 s100, s86, 0x80
	s_addc_u32 s101, s87, 0
	s_add_i32 s19, s19, s4
	s_mov_b32 m0, s19
	ds_read_b128 v[200:203], v169 offset:49152
	ds_read_b128 v[204:207], v169 offset:50176
	ds_read_b128 v[208:211], v169 offset:51200
	ds_read_b128 v[212:215], v169 offset:52224
	ds_read_b128 v[216:219], v169 offset:53248
	ds_read_b128 v[220:223], v169 offset:54272
	ds_read_b128 v[224:227], v169 offset:55296
	ds_read_b128 v[228:231], v169 offset:56320
	global_load_lds_dwordx4 v130, s[98:99]
	s_add_i32 m0, s19, 0x2000
	s_add_u32 s12, s12, 0x40080
	s_addc_u32 s13, s13, 0
	s_add_i32 s19, s22, s4
	global_load_lds_dwordx4 v134, s[98:99]
	s_mov_b32 m0, s19
	s_nop 0
	global_load_lds_dwordx4 v130, s[12:13]
	s_add_i32 m0, s19, 0x2000
	s_nop 0
	global_load_lds_dwordx4 v134, s[12:13]
	s_mov_b32 m0, s16
	s_nop 0
	global_load_lds_dwordx4 v128, s[100:101]
	s_mov_b32 m0, s33
	s_nop 0
	global_load_lds_dwordx4 v132, s[100:101]
	s_waitcnt vmcnt(8)
	s_waitcnt lgkmcnt(0)
	s_barrier
	s_setprio 1
	s_waitcnt lgkmcnt(0)
	v_mfma_f32_16x16x32_bf16 v[60:63], v[152:155], v[200:203], v[60:63]
	v_mfma_f32_16x16x32_bf16 v[56:59], v[162:165], v[200:203], v[56:59]
	v_mfma_f32_16x16x32_bf16 v[44:47], v[152:155], v[208:211], v[44:47]
	v_mfma_f32_16x16x32_bf16 v[40:43], v[162:165], v[208:211], v[40:43]
	v_mfma_f32_16x16x32_bf16 v[28:31], v[152:155], v[216:219], v[28:31]
	v_mfma_f32_16x16x32_bf16 v[24:27], v[162:165], v[216:219], v[24:27]
	v_mfma_f32_16x16x32_bf16 v[12:15], v[152:155], v[224:227], v[12:15]
	v_mfma_f32_16x16x32_bf16 v[8:11], v[162:165], v[224:227], v[8:11]
	v_mfma_f32_16x16x32_bf16 v[60:63], v[156:159], v[204:207], v[60:63]
	v_mfma_f32_16x16x32_bf16 v[56:59], v[180:183], v[204:207], v[56:59]
	v_mfma_f32_16x16x32_bf16 v[44:47], v[156:159], v[212:215], v[44:47]
	v_mfma_f32_16x16x32_bf16 v[40:43], v[180:183], v[212:215], v[40:43]
	v_mfma_f32_16x16x32_bf16 v[28:31], v[156:159], v[220:223], v[28:31]
	v_mfma_f32_16x16x32_bf16 v[24:27], v[180:183], v[220:223], v[24:27]
	v_mfma_f32_16x16x32_bf16 v[12:15], v[156:159], v[228:231], v[12:15]
	v_mfma_f32_16x16x32_bf16 v[8:11], v[180:183], v[228:231], v[8:11]
	s_setprio 0
	s_setprio 1
	v_mfma_f32_16x16x32_bf16 v[52:55], v[184:187], v[200:203], v[52:55]
	v_mfma_f32_16x16x32_bf16 v[48:51], v[192:195], v[200:203], v[48:51]
	v_mfma_f32_16x16x32_bf16 v[36:39], v[184:187], v[208:211], v[36:39]
	v_mfma_f32_16x16x32_bf16 v[32:35], v[192:195], v[208:211], v[32:35]
	v_mfma_f32_16x16x32_bf16 v[20:23], v[184:187], v[216:219], v[20:23]
	v_mfma_f32_16x16x32_bf16 v[16:19], v[192:195], v[216:219], v[16:19]
	v_mfma_f32_16x16x32_bf16 v[4:7], v[184:187], v[224:227], v[4:7]
	v_mfma_f32_16x16x32_bf16 v[0:3], v[192:195], v[224:227], v[0:3]
	v_mfma_f32_16x16x32_bf16 v[52:55], v[188:191], v[204:207], v[52:55]
	v_mfma_f32_16x16x32_bf16 v[48:51], v[196:199], v[204:207], v[48:51]
	v_mfma_f32_16x16x32_bf16 v[36:39], v[188:191], v[212:215], v[36:39]
	v_mfma_f32_16x16x32_bf16 v[32:35], v[196:199], v[212:215], v[32:35]
	v_mfma_f32_16x16x32_bf16 v[20:23], v[188:191], v[220:223], v[20:23]
	v_mfma_f32_16x16x32_bf16 v[16:19], v[196:199], v[220:223], v[16:19]
	v_mfma_f32_16x16x32_bf16 v[4:7], v[188:191], v[228:231], v[4:7]
	v_mfma_f32_16x16x32_bf16 v[0:3], v[196:199], v[228:231], v[0:3]
	s_add_i32 s17, s17, 2
	s_add_u32 s10, s10, 0x100
	s_addc_u32 s11, s11, 0
	s_add_u32 s7, s7, 0x100
	s_addc_u32 s15, s15, 0
	s_cmp_gt_u32 s17, 13
	s_setprio 0
	s_barrier
	s_cbranch_scc0 .LBB0_414
	s_and_b64 vcc, exec, s[58:59]
	s_cbranch_vccz .LBB0_417
	s_barrier

; #define PG8_STAGE(bufoff, gbase, voff) do { _Pragma("unroll") for (int _i = 0; _i < 2; ++_i) \
;         __builtin_amdgcn_global_load_lds((const unsigned*)((const char*)(gbase) + (voff)[_i]), (LAS unsigned*)(lds + (bufoff) + ldsw + _i * 8192), 16, 0, 0); } while (0)
; #define PG8_LDA(dst, b, h) do { _Pragma("unroll") for (int m = 0; m < 4; ++m) _Pragma("unroll") for (int k = 0; k < 2; ++k) dst[m][k] = *(const LAS bf16x8*)(lds + PG8_SA(b, h) + aoff + m * 2048 + k * 1024); } while (0)
; #define PG8_LDB(dst, b, h) do { _Pragma("unroll") for (int n = 0; n < 2; ++n) _Pragma("unroll") for (int k = 0; k < 2; ++k) dst[n][k] = *(const LAS bf16x8*)(lds + PG8_SB(b, h) + boff + n * 2048 + k * 1024); } while (0)
; #define PG8_MMA(ai, bj, At, Bt) do { __builtin_amdgcn_s_setprio(1); _Pragma("unroll") for (int m = 0; m < 4; ++m) _Pragma("unroll") for (int n = 0; n < 2; ++n) _Pragma("unroll") for (int k = 0; k < 2; ++k) \
;         acc[ai][bj][m][n] = __builtin_amdgcn_mfma_f32_16x16x32_bf16(Bt[n][k], At[m][k], acc[ai][bj][m][n], 0, 0, 0); __builtin_amdgcn_s_setprio(0); } while (0)
; #define PG8_WAIT_V(n) asm volatile("s_waitcnt vmcnt(" #n ")" ::: "memory")
; #define PG8_WAIT_L(n) asm volatile("s_waitcnt lgkmcnt(" #n ")" ::: "memory")
; #define PG8_BAR __builtin_amdgcn_s_barrier()
; #define PG8_SCHED __builtin_amdgcn_sched_barrier(0)
; template <class Epi>
; __device__ __forceinline__ void gemm_phase(LAS unsigned char* lds, const Gemm g, const StaticOrder& S, const Epi& E) {
;     ...
;             PG8_LDB(B0, 0, 0); PG8_LDB(B1, 0, 1); PG8_SCHED; PG8_LDA(At, 0, 0); PG8_STAGE(PG8_SA(1, 1), a1 + hsA, voffA);
;             PG8_WAIT_V(8); PG8_WAIT_L(0); PG8_BAR; PG8_MMA(0, 0, At, B0); PG8_MMA(0, 1, At, B1); PG8_BAR; PG8_SCHED;
;             PG8_LDA(At, 0, 1); PG8_STAGE(PG8_SB(0, 0), b2, voffB); PG8_STAGE(PG8_SB(0, 1), b2 + hsB, voffB); PG8_STAGE(PG8_SA(0, 0), a2, voffA);
;             PG8_WAIT_V(8); PG8_WAIT_L(0); PG8_BAR; PG8_MMA(1, 0, At, B0); PG8_MMA(1, 1, At, B1); PG8_BAR; PG8_SCHED;
.LBB0_720:
	ds_read_b128 v[128:131], v182
	ds_read_b128 v[132:135], v182 offset:1024
	ds_read_b128 v[136:139], v182 offset:2048
	ds_read_b128 v[140:143], v182 offset:3072
	ds_read_b128 v[166:169], v183
	ds_read_b128 v[188:191], v183 offset:1024
	ds_read_b128 v[192:195], v183 offset:2048
	ds_read_b128 v[196:199], v183 offset:3072
	s_add_u32 s39, s62, 0xfffc0080
	s_addc_u32 s40, s63, -1
	s_cmp_eq_u32 s38, 12
	s_cselect_b32 s67, s6, s40
	s_cselect_b32 s66, s7, s39
	s_cselect_b32 s65, s15, s37
	s_cselect_b32 s64, s35, s36
	s_add_i32 m0, s4, 0xc000
	ds_read_b128 v[200:203], v184
	ds_read_b128 v[204:207], v184 offset:1024
	ds_read_b128 v[208:211], v184 offset:2048
	ds_read_b128 v[212:215], v184 offset:3072
	ds_read_b128 v[216:219], v184 offset:4096
	ds_read_b128 v[220:223], v184 offset:5120
	ds_read_b128 v[224:227], v184 offset:6144
	ds_read_b128 v[228:231], v184 offset:7168
	global_load_lds_dwordx4 v156, s[62:63]
	s_add_i32 m0, s4, 0xe000
	s_nop 0
	global_load_lds_dwordx4 v158, s[62:63]
	s_waitcnt vmcnt(8)
	s_waitcnt lgkmcnt(0)
	s_barrier
	s_setprio 1
	s_waitcnt lgkmcnt(0)
	v_mfma_f32_16x16x32_bf16 v[124:127], v[128:131], v[200:203], v[124:127]
	v_mfma_f32_16x16x32_bf16 v[120:123], v[136:139], v[200:203], v[120:123]
	v_mfma_f32_16x16x32_bf16 v[108:111], v[128:131], v[208:211], v[108:111]
	v_mfma_f32_16x16x32_bf16 v[104:107], v[136:139], v[208:211], v[104:107]
	v_mfma_f32_16x16x32_bf16 v[92:95], v[128:131], v[216:219], v[92:95]
	v_mfma_f32_16x16x32_bf16 v[88:91], v[136:139], v[216:219], v[88:91]
	v_mfma_f32_16x16x32_bf16 v[76:79], v[128:131], v[224:227], v[76:79]
	v_mfma_f32_16x16x32_bf16 v[72:75], v[136:139], v[224:227], v[72:75]
	v_mfma_f32_16x16x32_bf16 v[124:127], v[132:135], v[204:207], v[124:127]
	v_mfma_f32_16x16x32_bf16 v[120:123], v[140:143], v[204:207], v[120:123]
	v_mfma_f32_16x16x32_bf16 v[108:111], v[132:135], v[212:215], v[108:111]
	v_mfma_f32_16x16x32_bf16 v[104:107], v[140:143], v[212:215], v[104:107]
	v_mfma_f32_16x16x32_bf16 v[92:95], v[132:135], v[220:223], v[92:95]
	v_mfma_f32_16x16x32_bf16 v[88:91], v[140:143], v[220:223], v[88:91]
	v_mfma_f32_16x16x32_bf16 v[76:79], v[132:135], v[228:231], v[76:79]
	v_mfma_f32_16x16x32_bf16 v[72:75], v[140:143], v[228:231], v[72:75]
	s_setprio 0
	s_setprio 1
	v_mfma_f32_16x16x32_bf16 v[116:119], v[166:169], v[200:203], v[116:119]
	v_mfma_f32_16x16x32_bf16 v[112:115], v[192:195], v[200:203], v[112:115]
	v_mfma_f32_16x16x32_bf16 v[100:103], v[166:169], v[208:211], v[100:103]
	v_mfma_f32_16x16x32_bf16 v[96:99], v[192:195], v[208:211], v[96:99]
	v_mfma_f32_16x16x32_bf16 v[84:87], v[166:169], v[216:219], v[84:87]
	v_mfma_f32_16x16x32_bf16 v[80:83], v[192:195], v[216:219], v[80:83]
	v_mfma_f32_16x16x32_bf16 v[68:71], v[166:169], v[224:227], v[68:71]
	v_mfma_f32_16x16x32_bf16 v[64:67], v[192:195], v[224:227], v[64:67]
	v_mfma_f32_16x16x32_bf16 v[116:119], v[188:191], v[204:207], v[116:119]
	v_mfma_f32_16x16x32_bf16 v[112:115], v[196:199], v[204:207], v[112:115]
	v_mfma_f32_16x16x32_bf16 v[100:103], v[188:191], v[212:215], v[100:103]
	v_mfma_f32_16x16x32_bf16 v[96:99], v[196:199], v[212:215], v[96:99]
	v_mfma_f32_16x16x32_bf16 v[84:87], v[188:191], v[220:223], v[84:87]
	v_mfma_f32_16x16x32_bf16 v[80:83], v[196:199], v[220:223], v[80:83]
	v_mfma_f32_16x16x32_bf16 v[68:71], v[188:191], v[228:231], v[68:71]
	v_mfma_f32_16x16x32_bf16 v[64:67], v[196:199], v[228:231], v[64:67]
	s_setprio 0
	s_barrier
	s_add_i32 s39, s27, s3
	s_mov_b32 m0, s39
	ds_read_b128 v[200:203], v184 offset:16384
	ds_read_b128 v[204:207], v184 offset:17408
	ds_read_b128 v[208:211], v184 offset:18432
	ds_read_b128 v[212:215], v184 offset:19456
	ds_read_b128 v[216:219], v184 offset:20480
	ds_read_b128 v[220:223], v184 offset:21504
	ds_read_b128 v[224:227], v184 offset:22528
	ds_read_b128 v[228:231], v184 offset:23552
	global_load_lds_dwordx4 v146, s[64:65]
	s_add_i32 m0, s39, 0x2000
	s_add_u32 s40, s64, 0x40000
	s_addc_u32 s41, s65, 0
	s_add_i32 s39, s28, s3
	global_load_lds_dwordx4 v150, s[64:65]
	s_mov_b32 m0, s39
	s_nop 0
	global_load_lds_dwordx4 v146, s[40:41]
	s_add_i32 m0, s39, 0x2000
	s_nop 0
	global_load_lds_dwordx4 v150, s[40:41]
	s_mov_b32 m0, s4
	s_nop 0
	global_load_lds_dwordx4 v144, s[66:67]
	s_mov_b32 m0, s5
	s_nop 0
	global_load_lds_dwordx4 v148, s[66:67]
	s_waitcnt vmcnt(8)
	s_waitcnt lgkmcnt(0)
	s_barrier
	s_setprio 1
	s_waitcnt lgkmcnt(0)
	v_mfma_f32_16x16x32_bf16 v[60:63], v[128:131], v[200:203], v[60:63]
	v_mfma_f32_16x16x32_bf16 v[56:59], v[136:139], v[200:203], v[56:59]
	v_mfma_f32_16x16x32_bf16 v[44:47], v[128:131], v[208:211], v[44:47]
	v_mfma_f32_16x16x32_bf16 v[40:43], v[136:139], v[208:211], v[40:43]
	v_mfma_f32_16x16x32_bf16 v[28:31], v[128:131], v[216:219], v[28:31]
	v_mfma_f32_16x16x32_bf16 v[24:27], v[136:139], v[216:219], v[24:27]
	v_mfma_f32_16x16x32_bf16 v[12:15], v[128:131], v[224:227], v[12:15]
	v_mfma_f32_16x16x32_bf16 v[8:11], v[136:139], v[224:227], v[8:11]
	v_mfma_f32_16x16x32_bf16 v[60:63], v[132:135], v[204:207], v[60:63]
	v_mfma_f32_16x16x32_bf16 v[56:59], v[140:143], v[204:207], v[56:59]
	v_mfma_f32_16x16x32_bf16 v[44:47], v[132:135], v[212:215], v[44:47]
	v_mfma_f32_16x16x32_bf16 v[40:43], v[140:143], v[212:215], v[40:43]
	v_mfma_f32_16x16x32_bf16 v[28:31], v[132:135], v[220:223], v[28:31]
	v_mfma_f32_16x16x32_bf16 v[24:27], v[140:143], v[220:223], v[24:27]
	v_mfma_f32_16x16x32_bf16 v[12:15], v[132:135], v[228:231], v[12:15]
	v_mfma_f32_16x16x32_bf16 v[8:11], v[140:143], v[228:231], v[8:11]
	s_setprio 0
	s_setprio 1
	v_mfma_f32_16x16x32_bf16 v[52:55], v[166:169], v[200:203], v[52:55]
	v_mfma_f32_16x16x32_bf16 v[48:51], v[192:195], v[200:203], v[48:51]
	v_mfma_f32_16x16x32_bf16 v[36:39], v[166:169], v[208:211], v[36:39]
	v_mfma_f32_16x16x32_bf16 v[32:35], v[192:195], v[208:211], v[32:35]
	v_mfma_f32_16x16x32_bf16 v[20:23], v[166:169], v[216:219], v[20:23]
	v_mfma_f32_16x16x32_bf16 v[16:19], v[192:195], v[216:219], v[16:19]
	v_mfma_f32_16x16x32_bf16 v[4:7], v[166:169], v[224:227], v[4:7]
	v_mfma_f32_16x16x32_bf16 v[0:3], v[192:195], v[224:227], v[0:3]
	v_mfma_f32_16x16x32_bf16 v[52:55], v[188:191], v[204:207], v[52:55]
	v_mfma_f32_16x16x32_bf16 v[48:51], v[196:199], v[204:207], v[48:51]
	v_mfma_f32_16x16x32_bf16 v[36:39], v[188:191], v[212:215], v[36:39]
	v_mfma_f32_16x16x32_bf16 v[32:35], v[196:199], v[212:215], v[32:35]
	v_mfma_f32_16x16x32_bf16 v[20:23], v[188:191], v[220:223], v[20:23]
	v_mfma_f32_16x16x32_bf16 v[16:19], v[196:199], v[220:223], v[16:19]
	v_mfma_f32_16x16x32_bf16 v[4:7], v[188:191], v[228:231], v[4:7]
	v_mfma_f32_16x16x32_bf16 v[0:3], v[196:199], v[228:231], v[0:3]
	s_setprio 0
	s_barrier
; #define PG8_STAGE(bufoff, gbase, voff) do { _Pragma("unroll") for (int _i = 0; _i < 2; ++_i) \
;         __builtin_amdgcn_global_load_lds((const unsigned*)((const char*)(gbase) + (voff)[_i]), (LAS unsigned*)(lds + (bufoff) + ldsw + _i * 8192), 16, 0, 0); } while (0)
; #define PG8_LDA(dst, b, h) do { _Pragma("unroll") for (int m = 0; m < 4; ++m) _Pragma("unroll") for (int k = 0; k < 2; ++k) dst[m][k] = *(const LAS bf16x8*)(lds + PG8_SA(b, h) + aoff + m * 2048 + k * 1024); } while (0)
; #define PG8_LDB(dst, b, h) do { _Pragma("unroll") for (int n = 0; n < 2; ++n) _Pragma("unroll") for (int k = 0; k < 2; ++k) dst[n][k] = *(const LAS bf16x8*)(lds + PG8_SB(b, h) + boff + n * 2048 + k * 1024); } while (0)
; #define PG8_MMA(ai, bj, At, Bt) do { __builtin_amdgcn_s_setprio(1); _Pragma("unroll") for (int m = 0; m < 4; ++m) _Pragma("unroll") for (int n = 0; n < 2; ++n) _Pragma("unroll") for (int k = 0; k < 2; ++k) \
;         acc[ai][bj][m][n] = __builtin_amdgcn_mfma_f32_16x16x32_bf16(Bt[n][k], At[m][k], acc[ai][bj][m][n], 0, 0, 0); __builtin_amdgcn_s_setprio(0); } while (0)
; #define PG8_WAIT_V(n) asm volatile("s_waitcnt vmcnt(" #n ")" ::: "memory")
; #define PG8_WAIT_L(n) asm volatile("s_waitcnt lgkmcnt(" #n ")" ::: "memory")
; #define PG8_BAR __builtin_amdgcn_s_barrier()
; #define PG8_SCHED __builtin_amdgcn_sched_barrier(0)
; template <class Epi>
; __device__ __forceinline__ void gemm_phase(LAS unsigned char* lds, const Gemm g, const StaticOrder& S, const Epi& E) {
;     ...
;             PG8_LDB(B0, 1, 0); PG8_LDB(B1, 1, 1); PG8_SCHED; PG8_LDA(At, 1, 0); PG8_STAGE(PG8_SA(0, 1), a2 + hsA, voffA);
;             PG8_WAIT_V(8); PG8_WAIT_L(0); PG8_BAR; PG8_MMA(0, 0, At, B0); PG8_MMA(0, 1, At, B1); PG8_BAR; PG8_SCHED;
;             PG8_LDA(At, 1, 1); PG8_STAGE(PG8_SB(1, 0), b3, voffB); PG8_STAGE(PG8_SB(1, 1), b3 + hsB, voffB); PG8_STAGE(PG8_SA(1, 0), a3, voffA);
;             PG8_WAIT_V(8); PG8_WAIT_L(0); PG8_BAR; PG8_MMA(1, 0, At, B0); PG8_MMA(1, 1, At, B1); PG8_BAR; PG8_SCHED;
;         }
	s_add_i32 s39, 0, 0x18000
	s_add_i32 s42, 0, 0x1c000
	v_add_u32_e32 v140, s39, v173
	v_add_u32_e32 v152, s42, v173
	ds_read_b128 v[128:131], v140
	ds_read_b128 v[132:135], v140 offset:1024
	ds_read_b128 v[136:139], v140 offset:2048
	ds_read_b128 v[140:143], v140 offset:3072
	ds_read_b128 v[166:169], v152
	ds_read_b128 v[188:191], v152 offset:1024
	ds_read_b128 v[192:195], v152 offset:2048
	ds_read_b128 v[196:199], v152 offset:3072
	s_add_u32 s40, s66, 0x40000
	s_addc_u32 s41, s67, 0
	s_mov_b32 m0, s16
	ds_read_b128 v[200:203], v184 offset:32768
	ds_read_b128 v[204:207], v184 offset:33792
	ds_read_b128 v[208:211], v184 offset:34816
	ds_read_b128 v[212:215], v184 offset:35840
	ds_read_b128 v[216:219], v184 offset:36864
	ds_read_b128 v[220:223], v184 offset:37888
	ds_read_b128 v[224:227], v184 offset:38912
	ds_read_b128 v[228:231], v184 offset:39936
	global_load_lds_dwordx4 v144, s[40:41]
	s_mov_b32 m0, s17
	s_nop 0
	global_load_lds_dwordx4 v148, s[40:41]
	s_waitcnt vmcnt(8)
	s_waitcnt lgkmcnt(0)
	s_barrier
	s_setprio 1
	s_waitcnt lgkmcnt(0)
	v_mfma_f32_16x16x32_bf16 v[124:127], v[128:131], v[200:203], v[124:127]
	v_mfma_f32_16x16x32_bf16 v[120:123], v[136:139], v[200:203], v[120:123]
	v_mfma_f32_16x16x32_bf16 v[108:111], v[128:131], v[208:211], v[108:111]
	v_mfma_f32_16x16x32_bf16 v[104:107], v[136:139], v[208:211], v[104:107]
	v_mfma_f32_16x16x32_bf16 v[92:95], v[128:131], v[216:219], v[92:95]
	v_mfma_f32_16x16x32_bf16 v[88:91], v[136:139], v[216:219], v[88:91]
	v_mfma_f32_16x16x32_bf16 v[76:79], v[128:131], v[224:227], v[76:79]
	v_mfma_f32_16x16x32_bf16 v[72:75], v[136:139], v[224:227], v[72:75]
	v_mfma_f32_16x16x32_bf16 v[124:127], v[132:135], v[204:207], v[124:127]
	v_mfma_f32_16x16x32_bf16 v[120:123], v[140:143], v[204:207], v[120:123]
	v_mfma_f32_16x16x32_bf16 v[108:111], v[132:135], v[212:215], v[108:111]
	v_mfma_f32_16x16x32_bf16 v[104:107], v[140:143], v[212:215], v[104:107]
	v_mfma_f32_16x16x32_bf16 v[92:95], v[132:135], v[220:223], v[92:95]
	v_mfma_f32_16x16x32_bf16 v[88:91], v[140:143], v[220:223], v[88:91]
	v_mfma_f32_16x16x32_bf16 v[76:79], v[132:135], v[228:231], v[76:79]
	v_mfma_f32_16x16x32_bf16 v[72:75], v[140:143], v[228:231], v[72:75]
	s_setprio 0
	s_setprio 1
	v_mfma_f32_16x16x32_bf16 v[116:119], v[166:169], v[200:203], v[116:119]
	v_mfma_f32_16x16x32_bf16 v[112:115], v[192:195], v[200:203], v[112:115]
	v_mfma_f32_16x16x32_bf16 v[100:103], v[166:169], v[208:211], v[100:103]
	v_mfma_f32_16x16x32_bf16 v[96:99], v[192:195], v[208:211], v[96:99]
	v_mfma_f32_16x16x32_bf16 v[84:87], v[166:169], v[216:219], v[84:87]
	v_mfma_f32_16x16x32_bf16 v[80:83], v[192:195], v[216:219], v[80:83]
	v_mfma_f32_16x16x32_bf16 v[68:71], v[166:169], v[224:227], v[68:71]
	v_mfma_f32_16x16x32_bf16 v[64:67], v[192:195], v[224:227], v[64:67]
	v_mfma_f32_16x16x32_bf16 v[116:119], v[188:191], v[204:207], v[116:119]
	v_mfma_f32_16x16x32_bf16 v[112:115], v[196:199], v[204:207], v[112:115]
	v_mfma_f32_16x16x32_bf16 v[100:103], v[188:191], v[212:215], v[100:103]
	v_mfma_f32_16x16x32_bf16 v[96:99], v[196:199], v[212:215], v[96:99]
	v_mfma_f32_16x16x32_bf16 v[84:87], v[188:191], v[220:223], v[84:87]
	v_mfma_f32_16x16x32_bf16 v[80:83], v[196:199], v[220:223], v[80:83]
	v_mfma_f32_16x16x32_bf16 v[68:71], v[188:191], v[228:231], v[68:71]
	v_mfma_f32_16x16x32_bf16 v[64:67], v[196:199], v[228:231], v[64:67]
	s_setprio 0
	s_barrier
	s_add_u32 s98, s64, 0x80
	s_addc_u32 s99, s65, 0
	s_add_u32 s100, s66, 0x80
	s_addc_u32 s101, s67, 0
	s_add_i32 s39, s39, s3
	s_mov_b32 m0, s39
	ds_read_b128 v[200:203], v184 offset:49152
	ds_read_b128 v[204:207], v184 offset:50176
	ds_read_b128 v[208:211], v184 offset:51200
	ds_read_b128 v[212:215], v184 offset:52224
	ds_read_b128 v[216:219], v184 offset:53248
	ds_read_b128 v[220:223], v184 offset:54272
	ds_read_b128 v[224:227], v184 offset:55296
	ds_read_b128 v[228:231], v184 offset:56320
	global_load_lds_dwordx4 v146, s[98:99]
	s_add_i32 m0, s39, 0x2000
	s_add_u32 s40, s64, 0x40080
	s_addc_u32 s41, s65, 0
	s_add_i32 s39, s42, s3
	global_load_lds_dwordx4 v150, s[98:99]
	s_mov_b32 m0, s39
	s_nop 0
	global_load_lds_dwordx4 v146, s[40:41]
	s_add_i32 m0, s39, 0x2000
	s_nop 0
	global_load_lds_dwordx4 v150, s[40:41]
	s_mov_b32 m0, s22
	s_nop 0
	global_load_lds_dwordx4 v144, s[100:101]
	s_mov_b32 m0, s23
	s_nop 0
	global_load_lds_dwordx4 v148, s[100:101]
	s_waitcnt vmcnt(8)
	s_waitcnt lgkmcnt(0)
	s_barrier
	s_setprio 1
	s_waitcnt lgkmcnt(0)
	v_mfma_f32_16x16x32_bf16 v[60:63], v[128:131], v[200:203], v[60:63]
	v_mfma_f32_16x16x32_bf16 v[56:59], v[136:139], v[200:203], v[56:59]
	v_mfma_f32_16x16x32_bf16 v[44:47], v[128:131], v[208:211], v[44:47]
	v_mfma_f32_16x16x32_bf16 v[40:43], v[136:139], v[208:211], v[40:43]
	v_mfma_f32_16x16x32_bf16 v[28:31], v[128:131], v[216:219], v[28:31]
	v_mfma_f32_16x16x32_bf16 v[24:27], v[136:139], v[216:219], v[24:27]
	v_mfma_f32_16x16x32_bf16 v[12:15], v[128:131], v[224:227], v[12:15]
	v_mfma_f32_16x16x32_bf16 v[8:11], v[136:139], v[224:227], v[8:11]
	v_mfma_f32_16x16x32_bf16 v[60:63], v[132:135], v[204:207], v[60:63]
	v_mfma_f32_16x16x32_bf16 v[56:59], v[140:143], v[204:207], v[56:59]
	v_mfma_f32_16x16x32_bf16 v[44:47], v[132:135], v[212:215], v[44:47]
	v_mfma_f32_16x16x32_bf16 v[40:43], v[140:143], v[212:215], v[40:43]
	v_mfma_f32_16x16x32_bf16 v[28:31], v[132:135], v[220:223], v[28:31]
	v_mfma_f32_16x16x32_bf16 v[24:27], v[140:143], v[220:223], v[24:27]
	v_mfma_f32_16x16x32_bf16 v[12:15], v[132:135], v[228:231], v[12:15]
	v_mfma_f32_16x16x32_bf16 v[8:11], v[140:143], v[228:231], v[8:11]
	s_setprio 0
	s_setprio 1
	v_mfma_f32_16x16x32_bf16 v[52:55], v[166:169], v[200:203], v[52:55]
	v_mfma_f32_16x16x32_bf16 v[48:51], v[192:195], v[200:203], v[48:51]
	v_mfma_f32_16x16x32_bf16 v[36:39], v[166:169], v[208:211], v[36:39]
	v_mfma_f32_16x16x32_bf16 v[32:35], v[192:195], v[208:211], v[32:35]
	v_mfma_f32_16x16x32_bf16 v[20:23], v[166:169], v[216:219], v[20:23]
	v_mfma_f32_16x16x32_bf16 v[16:19], v[192:195], v[216:219], v[16:19]
	v_mfma_f32_16x16x32_bf16 v[4:7], v[166:169], v[224:227], v[4:7]
	v_mfma_f32_16x16x32_bf16 v[0:3], v[192:195], v[224:227], v[0:3]
	v_mfma_f32_16x16x32_bf16 v[52:55], v[188:191], v[204:207], v[52:55]
	v_mfma_f32_16x16x32_bf16 v[48:51], v[196:199], v[204:207], v[48:51]
	v_mfma_f32_16x16x32_bf16 v[36:39], v[188:191], v[212:215], v[36:39]
	v_mfma_f32_16x16x32_bf16 v[32:35], v[196:199], v[212:215], v[32:35]
	v_mfma_f32_16x16x32_bf16 v[20:23], v[188:191], v[220:223], v[20:23]
	v_mfma_f32_16x16x32_bf16 v[16:19], v[196:199], v[220:223], v[16:19]
	v_mfma_f32_16x16x32_bf16 v[4:7], v[188:191], v[228:231], v[4:7]
	v_mfma_f32_16x16x32_bf16 v[0:3], v[196:199], v[228:231], v[0:3]
	s_add_i32 s38, s38, 2
	s_add_u32 s62, s62, 0x100
	s_addc_u32 s63, s63, 0
	s_add_u32 s36, s36, 0x100
	s_addc_u32 s37, s37, 0
	s_cmp_gt_u32 s38, 13
	s_setprio 0
	s_barrier
	s_cbranch_scc0 .LBB0_720
	s_and_b64 vcc, exec, s[12:13]
	s_cbranch_vccz .LBB0_723
	s_barrier

; #define DMA_T(s_) do { DMA_K(s_); DMA_V(s_); } while (0)
; #define WAIT_BAR() do { asm volatile("s_waitcnt vmcnt(0) lgkmcnt(0)" ::: "memory"); __builtin_amdgcn_s_barrier(); asm volatile("" ::: "memory"); } while (0)
; #define CLASSIFY(kv0_, act_, cls_) do { act_ = true; if (SWA) act_ = ((kv0_) + 63 >= qw - 128) && ((kv0_) <= qw + 159); \
;         cls_ = 0; if ((kv0_) + 63 < qw) cls_ = 1; else if ((kv0_) > qw + 31) cls_ = 2; \
;         if (SWA) { if (cls_ == 1 && qw + 31 - (kv0_) > 128) cls_ = 0; if (cls_ == 2 && (kv0_) + 63 - qw > 128) cls_ = 0; } } while (0)
; template <bool SWA>
; __device__ __forceinline__ void unit(LAS unsigned char* lds, const bf16_t* PROJ, const bf16_t* KT, const bf16_t* VT, bf16_t* OB, int opitch, int ocol, int b, int head, int qb, float slope2, float m_init, float lam, const float* subg) {
;     ...
;     for (int S = 0; S < npairs; ++S) {
;         const int sa = 2 * S, sb = 2 * S + 1;
;         if (sa + 2 < nsteps) DMA_T(sa + 2);
;         if (sb + 2 < nsteps) DMA_T(sb + 2);
;         const int kva = TILE_OF(sa) * 64, kvb = TILE_OF(sb < nsteps ? sb : sa) * 64;
;         bool acta, actb; int clsa, clsb;
;         CLASSIFY(kva, acta, clsa); CLASSIFY(kvb, actb, clsb); actb = actb && (sb < nsteps);
;         f32x16 s0, s1, u0, u1;
;         if (acta) QK_T(s0, s1, sa, clsa);
;         if (actb) QK_T(u0, u1, sb, clsb);
;         if (acta) { SM_T(s0, s1, kva, clsa); if (pvalid) PV_TILE(sa); }
;         if (actb) { SM_T(u0, u1, kvb, clsb); if (pvalid) PV_TILE(sb); }
;         WAIT_BAR();
.LBB0_883:
	s_add_i32 s1, s1, 2
	s_add_i32 s25, s25, 0x8000
	s_cmp_eq_u32 s1, 33
	s_waitcnt vmcnt(0) lgkmcnt(0)
	s_barrier
	s_cbranch_scc1 .LBB0_917

; #define PG8_STAGE(bufoff, gbase, voff) do { _Pragma("unroll") for (int _i = 0; _i < 2; ++_i) \
;         __builtin_amdgcn_global_load_lds((const unsigned*)((const char*)(gbase) + (voff)[_i]), (LAS unsigned*)(lds + (bufoff) + ldsw + _i * 8192), 16, 0, 0); } while (0)
; #define PG8_LDA(dst, b, h) do { _Pragma("unroll") for (int m = 0; m < 4; ++m) _Pragma("unroll") for (int k = 0; k < 2; ++k) dst[m][k] = *(const LAS bf16x8*)(lds + PG8_SA(b, h) + aoff + m * 2048 + k * 1024); } while (0)
; #define PG8_LDB(dst, b, h) do { _Pragma("unroll") for (int n = 0; n < 2; ++n) _Pragma("unroll") for (int k = 0; k < 2; ++k) dst[n][k] = *(const LAS bf16x8*)(lds + PG8_SB(b, h) + boff + n * 2048 + k * 1024); } while (0)
; #define PG8_MMA(ai, bj, At, Bt) do { __builtin_amdgcn_s_setprio(1); _Pragma("unroll") for (int m = 0; m < 4; ++m) _Pragma("unroll") for (int n = 0; n < 2; ++n) _Pragma("unroll") for (int k = 0; k < 2; ++k) \
;         acc[ai][bj][m][n] = __builtin_amdgcn_mfma_f32_16x16x32_bf16(Bt[n][k], At[m][k], acc[ai][bj][m][n], 0, 0, 0); __builtin_amdgcn_s_setprio(0); } while (0)
; #define PG8_WAIT_V(n) asm volatile("s_waitcnt vmcnt(" #n ")" ::: "memory")
; #define PG8_WAIT_L(n) asm volatile("s_waitcnt lgkmcnt(" #n ")" ::: "memory")
; #define PG8_BAR __builtin_amdgcn_s_barrier()
; #define PG8_SCHED __builtin_amdgcn_sched_barrier(0)
; template <class Epi>
; __device__ __forceinline__ void gemm_phase(LAS unsigned char* lds, const Gemm g, const StaticOrder& S, const Epi& E) {
;     ...
;             PG8_LDB(B0, 0, 0); PG8_LDB(B1, 0, 1); PG8_SCHED; PG8_LDA(At, 0, 0); PG8_STAGE(PG8_SA(1, 1), a1 + hsA, voffA);
;             PG8_WAIT_V(8); PG8_WAIT_L(0); PG8_BAR; PG8_MMA(0, 0, At, B0); PG8_MMA(0, 1, At, B1); PG8_BAR; PG8_SCHED;
;             PG8_LDA(At, 0, 1); PG8_STAGE(PG8_SB(0, 0), b2, voffB); PG8_STAGE(PG8_SB(0, 1), b2 + hsB, voffB); PG8_STAGE(PG8_SA(0, 0), a2, voffA);
;             PG8_WAIT_V(8); PG8_WAIT_L(0); PG8_BAR; PG8_MMA(1, 0, At, B0); PG8_MMA(1, 1, At, B1); PG8_BAR; PG8_SCHED;
.LBB0_1234:
	ds_read_b128 v[144:147], v155
	ds_read_b128 v[148:151], v155 offset:1024
	ds_read_b128 v[162:165], v155 offset:2048
	ds_read_b128 v[166:169], v155 offset:3072
	ds_read_b128 v[170:173], v156
	ds_read_b128 v[174:177], v156 offset:1024
	ds_read_b128 v[184:187], v156 offset:2048
	ds_read_b128 v[188:191], v156 offset:3072
	s_add_u32 s39, s48, 0xfffc0080
	s_addc_u32 s41, s49, -1
	s_cmp_eq_u32 s35, 12
	s_cselect_b32 s53, s0, s41
	s_cselect_b32 s52, s1, s39
	s_cselect_b32 s51, s6, s34
	s_cselect_b32 s50, s7, s13
	s_add_i32 m0, s5, 0xc000
	ds_read_b128 v[192:195], v157
	ds_read_b128 v[196:199], v157 offset:1024
	ds_read_b128 v[200:203], v157 offset:2048
	ds_read_b128 v[204:207], v157 offset:3072
	ds_read_b128 v[208:211], v157 offset:4096
	ds_read_b128 v[212:215], v157 offset:5120
	ds_read_b128 v[216:219], v157 offset:6144
	ds_read_b128 v[220:223], v157 offset:7168
	global_load_lds_dwordx4 v136, s[48:49]
	s_add_i32 m0, s5, 0xe000
	s_nop 0
	global_load_lds_dwordx4 v138, s[48:49]
	s_waitcnt vmcnt(8)
	s_waitcnt lgkmcnt(0)
	s_barrier
	s_setprio 1
	s_waitcnt lgkmcnt(0)
	v_mfma_f32_16x16x32_bf16 v[124:127], v[144:147], v[192:195], v[124:127]
	v_mfma_f32_16x16x32_bf16 v[120:123], v[162:165], v[192:195], v[120:123]
	v_mfma_f32_16x16x32_bf16 v[108:111], v[144:147], v[200:203], v[108:111]
	v_mfma_f32_16x16x32_bf16 v[104:107], v[162:165], v[200:203], v[104:107]
	v_mfma_f32_16x16x32_bf16 v[92:95], v[144:147], v[208:211], v[92:95]
	v_mfma_f32_16x16x32_bf16 v[88:91], v[162:165], v[208:211], v[88:91]
	v_mfma_f32_16x16x32_bf16 v[76:79], v[144:147], v[216:219], v[76:79]
	v_mfma_f32_16x16x32_bf16 v[72:75], v[162:165], v[216:219], v[72:75]
	v_mfma_f32_16x16x32_bf16 v[124:127], v[148:151], v[196:199], v[124:127]
	v_mfma_f32_16x16x32_bf16 v[120:123], v[166:169], v[196:199], v[120:123]
	v_mfma_f32_16x16x32_bf16 v[108:111], v[148:151], v[204:207], v[108:111]
	v_mfma_f32_16x16x32_bf16 v[104:107], v[166:169], v[204:207], v[104:107]
	v_mfma_f32_16x16x32_bf16 v[92:95], v[148:151], v[212:215], v[92:95]
	v_mfma_f32_16x16x32_bf16 v[88:91], v[166:169], v[212:215], v[88:91]
	v_mfma_f32_16x16x32_bf16 v[76:79], v[148:151], v[220:223], v[76:79]
	v_mfma_f32_16x16x32_bf16 v[72:75], v[166:169], v[220:223], v[72:75]
	s_setprio 0
	s_setprio 1
	v_mfma_f32_16x16x32_bf16 v[116:119], v[170:173], v[192:195], v[116:119]
	v_mfma_f32_16x16x32_bf16 v[112:115], v[184:187], v[192:195], v[112:115]
	v_mfma_f32_16x16x32_bf16 v[100:103], v[170:173], v[200:203], v[100:103]
	v_mfma_f32_16x16x32_bf16 v[96:99], v[184:187], v[200:203], v[96:99]
	v_mfma_f32_16x16x32_bf16 v[84:87], v[170:173], v[208:211], v[84:87]
	v_mfma_f32_16x16x32_bf16 v[80:83], v[184:187], v[208:211], v[80:83]
	v_mfma_f32_16x16x32_bf16 v[68:71], v[170:173], v[216:219], v[68:71]
	v_mfma_f32_16x16x32_bf16 v[64:67], v[184:187], v[216:219], v[64:67]
	v_mfma_f32_16x16x32_bf16 v[116:119], v[174:177], v[196:199], v[116:119]
	v_mfma_f32_16x16x32_bf16 v[112:115], v[188:191], v[196:199], v[112:115]
	v_mfma_f32_16x16x32_bf16 v[100:103], v[174:177], v[204:207], v[100:103]
	v_mfma_f32_16x16x32_bf16 v[96:99], v[188:191], v[204:207], v[96:99]
	v_mfma_f32_16x16x32_bf16 v[84:87], v[174:177], v[212:215], v[84:87]
	v_mfma_f32_16x16x32_bf16 v[80:83], v[188:191], v[212:215], v[80:83]
	v_mfma_f32_16x16x32_bf16 v[68:71], v[174:177], v[220:223], v[68:71]
	v_mfma_f32_16x16x32_bf16 v[64:67], v[188:191], v[220:223], v[64:67]
	s_setprio 0
	s_barrier
	s_add_i32 s39, s31, s4
	s_mov_b32 m0, s39
	ds_read_b128 v[192:195], v157 offset:16384
	ds_read_b128 v[196:199], v157 offset:17408
	ds_read_b128 v[200:203], v157 offset:18432
	ds_read_b128 v[204:207], v157 offset:19456
	ds_read_b128 v[208:211], v157 offset:20480
	ds_read_b128 v[212:215], v157 offset:21504
	ds_read_b128 v[216:219], v157 offset:22528
	ds_read_b128 v[220:223], v157 offset:23552
	global_load_lds_dwordx4 v130, s[50:51]
	s_add_i32 m0, s39, 0x2000
	s_add_u32 s54, s50, 0x40000
	s_addc_u32 s55, s51, 0
	s_add_i32 s39, s33, s4
	global_load_lds_dwordx4 v134, s[50:51]
	s_mov_b32 m0, s39
	s_nop 0
	global_load_lds_dwordx4 v130, s[54:55]
	s_add_i32 m0, s39, 0x2000
	s_nop 0
	global_load_lds_dwordx4 v134, s[54:55]
	s_mov_b32 m0, s5
	s_nop 0
	global_load_lds_dwordx4 v128, s[52:53]
	s_mov_b32 m0, s16
	s_nop 0
	global_load_lds_dwordx4 v132, s[52:53]
	s_waitcnt vmcnt(8)
	s_waitcnt lgkmcnt(0)
	s_barrier
	s_setprio 1
	s_waitcnt lgkmcnt(0)
	v_mfma_f32_16x16x32_bf16 v[60:63], v[144:147], v[192:195], v[60:63]
	v_mfma_f32_16x16x32_bf16 v[56:59], v[162:165], v[192:195], v[56:59]
	v_mfma_f32_16x16x32_bf16 v[44:47], v[144:147], v[200:203], v[44:47]
	v_mfma_f32_16x16x32_bf16 v[40:43], v[162:165], v[200:203], v[40:43]
	v_mfma_f32_16x16x32_bf16 v[28:31], v[144:147], v[208:211], v[28:31]
	v_mfma_f32_16x16x32_bf16 v[24:27], v[162:165], v[208:211], v[24:27]
	v_mfma_f32_16x16x32_bf16 v[12:15], v[144:147], v[216:219], v[12:15]
	v_mfma_f32_16x16x32_bf16 v[8:11], v[162:165], v[216:219], v[8:11]
	v_mfma_f32_16x16x32_bf16 v[60:63], v[148:151], v[196:199], v[60:63]
	v_mfma_f32_16x16x32_bf16 v[56:59], v[166:169], v[196:199], v[56:59]
	v_mfma_f32_16x16x32_bf16 v[44:47], v[148:151], v[204:207], v[44:47]
	v_mfma_f32_16x16x32_bf16 v[40:43], v[166:169], v[204:207], v[40:43]
	v_mfma_f32_16x16x32_bf16 v[28:31], v[148:151], v[212:215], v[28:31]
	v_mfma_f32_16x16x32_bf16 v[24:27], v[166:169], v[212:215], v[24:27]
	v_mfma_f32_16x16x32_bf16 v[12:15], v[148:151], v[220:223], v[12:15]
	v_mfma_f32_16x16x32_bf16 v[8:11], v[166:169], v[220:223], v[8:11]
	s_setprio 0
	s_setprio 1
	v_mfma_f32_16x16x32_bf16 v[52:55], v[170:173], v[192:195], v[52:55]
	v_mfma_f32_16x16x32_bf16 v[48:51], v[184:187], v[192:195], v[48:51]
	v_mfma_f32_16x16x32_bf16 v[36:39], v[170:173], v[200:203], v[36:39]
	v_mfma_f32_16x16x32_bf16 v[32:35], v[184:187], v[200:203], v[32:35]
	v_mfma_f32_16x16x32_bf16 v[20:23], v[170:173], v[208:211], v[20:23]
	v_mfma_f32_16x16x32_bf16 v[16:19], v[184:187], v[208:211], v[16:19]
	v_mfma_f32_16x16x32_bf16 v[4:7], v[170:173], v[216:219], v[4:7]
	v_mfma_f32_16x16x32_bf16 v[0:3], v[184:187], v[216:219], v[0:3]
	v_mfma_f32_16x16x32_bf16 v[52:55], v[174:177], v[196:199], v[52:55]
	v_mfma_f32_16x16x32_bf16 v[48:51], v[188:191], v[196:199], v[48:51]
	v_mfma_f32_16x16x32_bf16 v[36:39], v[174:177], v[204:207], v[36:39]
	v_mfma_f32_16x16x32_bf16 v[32:35], v[188:191], v[204:207], v[32:35]
	v_mfma_f32_16x16x32_bf16 v[20:23], v[174:177], v[212:215], v[20:23]
	v_mfma_f32_16x16x32_bf16 v[16:19], v[188:191], v[212:215], v[16:19]
	v_mfma_f32_16x16x32_bf16 v[4:7], v[174:177], v[220:223], v[4:7]
	v_mfma_f32_16x16x32_bf16 v[0:3], v[188:191], v[220:223], v[0:3]
	s_setprio 0
	s_barrier
; #define PG8_STAGE(bufoff, gbase, voff) do { _Pragma("unroll") for (int _i = 0; _i < 2; ++_i) \
;         __builtin_amdgcn_global_load_lds((const unsigned*)((const char*)(gbase) + (voff)[_i]), (LAS unsigned*)(lds + (bufoff) + ldsw + _i * 8192), 16, 0, 0); } while (0)
; #define PG8_LDA(dst, b, h) do { _Pragma("unroll") for (int m = 0; m < 4; ++m) _Pragma("unroll") for (int k = 0; k < 2; ++k) dst[m][k] = *(const LAS bf16x8*)(lds + PG8_SA(b, h) + aoff + m * 2048 + k * 1024); } while (0)
; #define PG8_LDB(dst, b, h) do { _Pragma("unroll") for (int n = 0; n < 2; ++n) _Pragma("unroll") for (int k = 0; k < 2; ++k) dst[n][k] = *(const LAS bf16x8*)(lds + PG8_SB(b, h) + boff + n * 2048 + k * 1024); } while (0)
; #define PG8_MMA(ai, bj, At, Bt) do { __builtin_amdgcn_s_setprio(1); _Pragma("unroll") for (int m = 0; m < 4; ++m) _Pragma("unroll") for (int n = 0; n < 2; ++n) _Pragma("unroll") for (int k = 0; k < 2; ++k) \
;         acc[ai][bj][m][n] = __builtin_amdgcn_mfma_f32_16x16x32_bf16(Bt[n][k], At[m][k], acc[ai][bj][m][n], 0, 0, 0); __builtin_amdgcn_s_setprio(0); } while (0)
; #define PG8_WAIT_V(n) asm volatile("s_waitcnt vmcnt(" #n ")" ::: "memory")
; #define PG8_WAIT_L(n) asm volatile("s_waitcnt lgkmcnt(" #n ")" ::: "memory")
; #define PG8_BAR __builtin_amdgcn_s_barrier()
; #define PG8_SCHED __builtin_amdgcn_sched_barrier(0)
; template <class Epi>
; __device__ __forceinline__ void gemm_phase(LAS unsigned char* lds, const Gemm g, const StaticOrder& S, const Epi& E) {
;     ...
;             PG8_LDB(B0, 1, 0); PG8_LDB(B1, 1, 1); PG8_SCHED; PG8_LDA(At, 1, 0); PG8_STAGE(PG8_SA(0, 1), a2 + hsA, voffA);
;             PG8_WAIT_V(8); PG8_WAIT_L(0); PG8_BAR; PG8_MMA(0, 0, At, B0); PG8_MMA(0, 1, At, B1); PG8_BAR; PG8_SCHED;
;             PG8_LDA(At, 1, 1); PG8_STAGE(PG8_SB(1, 0), b3, voffB); PG8_STAGE(PG8_SB(1, 1), b3 + hsB, voffB); PG8_STAGE(PG8_SA(1, 0), a3, voffA);
;             PG8_WAIT_V(8); PG8_WAIT_L(0); PG8_BAR; PG8_MMA(1, 0, At, B0); PG8_MMA(1, 1, At, B1); PG8_BAR; PG8_SCHED;
;         }
	s_add_i32 s39, 0, 0x18000
	v_add_u32_e32 v160, s39, v153
	s_add_i32 s41, 0, 0x1c000
	ds_read_b128 v[144:147], v160
	ds_read_b128 v[148:151], v160 offset:1024
	ds_read_b128 v[162:165], v160 offset:2048
	ds_read_b128 v[166:169], v160 offset:3072
	v_add_u32_e32 v160, s41, v153
	ds_read_b128 v[170:173], v160
	ds_read_b128 v[174:177], v160 offset:1024
	ds_read_b128 v[184:187], v160 offset:2048
	ds_read_b128 v[188:191], v160 offset:3072
	s_add_u32 s52, s52, 0x40000
	s_addc_u32 s53, s53, 0
	s_mov_b32 m0, s17
	ds_read_b128 v[192:195], v157 offset:32768
	ds_read_b128 v[196:199], v157 offset:33792
	ds_read_b128 v[200:203], v157 offset:34816
	ds_read_b128 v[204:207], v157 offset:35840
	ds_read_b128 v[208:211], v157 offset:36864
	ds_read_b128 v[212:215], v157 offset:37888
	ds_read_b128 v[216:219], v157 offset:38912
	ds_read_b128 v[220:223], v157 offset:39936
	global_load_lds_dwordx4 v128, s[52:53]
	s_mov_b32 m0, s18
	s_nop 0
	global_load_lds_dwordx4 v132, s[52:53]
	s_waitcnt vmcnt(8)
	s_waitcnt lgkmcnt(0)
	s_barrier
	s_setprio 1
	s_waitcnt lgkmcnt(0)
	v_mfma_f32_16x16x32_bf16 v[124:127], v[144:147], v[192:195], v[124:127]
	v_mfma_f32_16x16x32_bf16 v[120:123], v[162:165], v[192:195], v[120:123]
	v_mfma_f32_16x16x32_bf16 v[108:111], v[144:147], v[200:203], v[108:111]
	v_mfma_f32_16x16x32_bf16 v[104:107], v[162:165], v[200:203], v[104:107]
	v_mfma_f32_16x16x32_bf16 v[92:95], v[144:147], v[208:211], v[92:95]
	v_mfma_f32_16x16x32_bf16 v[88:91], v[162:165], v[208:211], v[88:91]
	v_mfma_f32_16x16x32_bf16 v[76:79], v[144:147], v[216:219], v[76:79]
	v_mfma_f32_16x16x32_bf16 v[72:75], v[162:165], v[216:219], v[72:75]
	v_mfma_f32_16x16x32_bf16 v[124:127], v[148:151], v[196:199], v[124:127]
	v_mfma_f32_16x16x32_bf16 v[120:123], v[166:169], v[196:199], v[120:123]
	v_mfma_f32_16x16x32_bf16 v[108:111], v[148:151], v[204:207], v[108:111]
	v_mfma_f32_16x16x32_bf16 v[104:107], v[166:169], v[204:207], v[104:107]
	v_mfma_f32_16x16x32_bf16 v[92:95], v[148:151], v[212:215], v[92:95]
	v_mfma_f32_16x16x32_bf16 v[88:91], v[166:169], v[212:215], v[88:91]
	v_mfma_f32_16x16x32_bf16 v[76:79], v[148:151], v[220:223], v[76:79]
	v_mfma_f32_16x16x32_bf16 v[72:75], v[166:169], v[220:223], v[72:75]
	s_setprio 0
	s_setprio 1
	v_mfma_f32_16x16x32_bf16 v[116:119], v[170:173], v[192:195], v[116:119]
	v_mfma_f32_16x16x32_bf16 v[112:115], v[184:187], v[192:195], v[112:115]
	v_mfma_f32_16x16x32_bf16 v[100:103], v[170:173], v[200:203], v[100:103]
	v_mfma_f32_16x16x32_bf16 v[96:99], v[184:187], v[200:203], v[96:99]
	v_mfma_f32_16x16x32_bf16 v[84:87], v[170:173], v[208:211], v[84:87]
	v_mfma_f32_16x16x32_bf16 v[80:83], v[184:187], v[208:211], v[80:83]
	v_mfma_f32_16x16x32_bf16 v[68:71], v[170:173], v[216:219], v[68:71]
	v_mfma_f32_16x16x32_bf16 v[64:67], v[184:187], v[216:219], v[64:67]
	v_mfma_f32_16x16x32_bf16 v[116:119], v[174:177], v[196:199], v[116:119]
	v_mfma_f32_16x16x32_bf16 v[112:115], v[188:191], v[196:199], v[112:115]
	v_mfma_f32_16x16x32_bf16 v[100:103], v[174:177], v[204:207], v[100:103]
	v_mfma_f32_16x16x32_bf16 v[96:99], v[188:191], v[204:207], v[96:99]
	v_mfma_f32_16x16x32_bf16 v[84:87], v[174:177], v[212:215], v[84:87]
	v_mfma_f32_16x16x32_bf16 v[80:83], v[188:191], v[212:215], v[80:83]
	v_mfma_f32_16x16x32_bf16 v[68:71], v[174:177], v[220:223], v[68:71]
	v_mfma_f32_16x16x32_bf16 v[64:67], v[188:191], v[220:223], v[64:67]
	s_setprio 0
	s_barrier
	s_add_u32 s98, s50, 0x80
	s_addc_u32 s99, s51, 0
	s_add_u32 s100, s52, 0xfffc0080
	s_addc_u32 s101, s53, -1
	s_add_i32 s39, s39, s4
	s_mov_b32 m0, s39
	ds_read_b128 v[192:195], v157 offset:49152
	ds_read_b128 v[196:199], v157 offset:50176
	ds_read_b128 v[200:203], v157 offset:51200
	ds_read_b128 v[204:207], v157 offset:52224
	ds_read_b128 v[208:211], v157 offset:53248
	ds_read_b128 v[212:215], v157 offset:54272
	ds_read_b128 v[216:219], v157 offset:55296
	ds_read_b128 v[220:223], v157 offset:56320
	global_load_lds_dwordx4 v130, s[98:99]
	s_add_i32 m0, s39, 0x2000
	s_add_u32 s50, s50, 0x40080
	s_addc_u32 s51, s51, 0
	s_add_i32 s39, s41, s4
	global_load_lds_dwordx4 v134, s[98:99]
	s_mov_b32 m0, s39
	s_nop 0
	global_load_lds_dwordx4 v130, s[50:51]
	s_add_i32 m0, s39, 0x2000
	s_nop 0
	global_load_lds_dwordx4 v134, s[50:51]
	s_mov_b32 m0, s22
	s_nop 0
	global_load_lds_dwordx4 v128, s[100:101]
	s_mov_b32 m0, s23
	s_nop 0
	global_load_lds_dwordx4 v132, s[100:101]
	s_waitcnt vmcnt(8)
	s_waitcnt lgkmcnt(0)
	s_barrier
	s_setprio 1
	s_waitcnt lgkmcnt(0)
	v_mfma_f32_16x16x32_bf16 v[60:63], v[144:147], v[192:195], v[60:63]
	v_mfma_f32_16x16x32_bf16 v[56:59], v[162:165], v[192:195], v[56:59]
	v_mfma_f32_16x16x32_bf16 v[44:47], v[144:147], v[200:203], v[44:47]
	v_mfma_f32_16x16x32_bf16 v[40:43], v[162:165], v[200:203], v[40:43]
	v_mfma_f32_16x16x32_bf16 v[28:31], v[144:147], v[208:211], v[28:31]
	v_mfma_f32_16x16x32_bf16 v[24:27], v[162:165], v[208:211], v[24:27]
	v_mfma_f32_16x16x32_bf16 v[12:15], v[144:147], v[216:219], v[12:15]
	v_mfma_f32_16x16x32_bf16 v[8:11], v[162:165], v[216:219], v[8:11]
	v_mfma_f32_16x16x32_bf16 v[60:63], v[148:151], v[196:199], v[60:63]
	v_mfma_f32_16x16x32_bf16 v[56:59], v[166:169], v[196:199], v[56:59]
	v_mfma_f32_16x16x32_bf16 v[44:47], v[148:151], v[204:207], v[44:47]
	v_mfma_f32_16x16x32_bf16 v[40:43], v[166:169], v[204:207], v[40:43]
	v_mfma_f32_16x16x32_bf16 v[28:31], v[148:151], v[212:215], v[28:31]
	v_mfma_f32_16x16x32_bf16 v[24:27], v[166:169], v[212:215], v[24:27]
	v_mfma_f32_16x16x32_bf16 v[12:15], v[148:151], v[220:223], v[12:15]
	v_mfma_f32_16x16x32_bf16 v[8:11], v[166:169], v[220:223], v[8:11]
	s_setprio 0
	s_setprio 1
	v_mfma_f32_16x16x32_bf16 v[52:55], v[170:173], v[192:195], v[52:55]
	v_mfma_f32_16x16x32_bf16 v[48:51], v[184:187], v[192:195], v[48:51]
	v_mfma_f32_16x16x32_bf16 v[36:39], v[170:173], v[200:203], v[36:39]
	v_mfma_f32_16x16x32_bf16 v[32:35], v[184:187], v[200:203], v[32:35]
	v_mfma_f32_16x16x32_bf16 v[20:23], v[170:173], v[208:211], v[20:23]
	v_mfma_f32_16x16x32_bf16 v[16:19], v[184:187], v[208:211], v[16:19]
	v_mfma_f32_16x16x32_bf16 v[4:7], v[170:173], v[216:219], v[4:7]
	v_mfma_f32_16x16x32_bf16 v[0:3], v[184:187], v[216:219], v[0:3]
	v_mfma_f32_16x16x32_bf16 v[52:55], v[174:177], v[196:199], v[52:55]
	v_mfma_f32_16x16x32_bf16 v[48:51], v[188:191], v[196:199], v[48:51]
	v_mfma_f32_16x16x32_bf16 v[36:39], v[174:177], v[204:207], v[36:39]
	v_mfma_f32_16x16x32_bf16 v[32:35], v[188:191], v[204:207], v[32:35]
	v_mfma_f32_16x16x32_bf16 v[20:23], v[174:177], v[212:215], v[20:23]
	v_mfma_f32_16x16x32_bf16 v[16:19], v[188:191], v[212:215], v[16:19]
	v_mfma_f32_16x16x32_bf16 v[4:7], v[174:177], v[220:223], v[4:7]
	v_mfma_f32_16x16x32_bf16 v[0:3], v[188:191], v[220:223], v[0:3]
	s_add_i32 s35, s35, 2
	s_add_u32 s48, s48, 0x100
	s_addc_u32 s49, s49, 0
	s_add_u32 s13, s13, 0x100
	s_addc_u32 s34, s34, 0
	s_cmp_gt_u32 s35, 13
	s_setprio 0
	s_barrier
	s_cbranch_scc0 .LBB0_1234
	s_and_b64 vcc, exec, s[26:27]
	s_cbranch_vccz .LBB0_1237
	s_barrier

; #define PG8_STAGE(bufoff, gbase, voff) do { _Pragma("unroll") for (int _i = 0; _i < 2; ++_i) \
;         __builtin_amdgcn_global_load_lds((const unsigned*)((const char*)(gbase) + (voff)[_i]), (LAS unsigned*)(lds + (bufoff) + ldsw + _i * 8192), 16, 0, 0); } while (0)
; #define PG8_LDA(dst, b, h) do { _Pragma("unroll") for (int m = 0; m < 4; ++m) _Pragma("unroll") for (int k = 0; k < 2; ++k) dst[m][k] = *(const LAS bf16x8*)(lds + PG8_SA(b, h) + aoff + m * 2048 + k * 1024); } while (0)
; #define PG8_LDB(dst, b, h) do { _Pragma("unroll") for (int n = 0; n < 2; ++n) _Pragma("unroll") for (int k = 0; k < 2; ++k) dst[n][k] = *(const LAS bf16x8*)(lds + PG8_SB(b, h) + boff + n * 2048 + k * 1024); } while (0)
; #define PG8_MMA(ai, bj, At, Bt) do { __builtin_amdgcn_s_setprio(1); _Pragma("unroll") for (int m = 0; m < 4; ++m) _Pragma("unroll") for (int n = 0; n < 2; ++n) _Pragma("unroll") for (int k = 0; k < 2; ++k) \
;         acc[ai][bj][m][n] = __builtin_amdgcn_mfma_f32_16x16x32_bf16(Bt[n][k], At[m][k], acc[ai][bj][m][n], 0, 0, 0); __builtin_amdgcn_s_setprio(0); } while (0)
; #define PG8_WAIT_V(n) asm volatile("s_waitcnt vmcnt(" #n ")" ::: "memory")
; #define PG8_WAIT_L(n) asm volatile("s_waitcnt lgkmcnt(" #n ")" ::: "memory")
; #define PG8_BAR __builtin_amdgcn_s_barrier()
; #define PG8_SCHED __builtin_amdgcn_sched_barrier(0)
; template <class Epi>
; __device__ __forceinline__ void gemm_phase(LAS unsigned char* lds, const Gemm g, const StaticOrder& S, const Epi& E) {
;     ...
;             PG8_LDB(B0, 0, 0); PG8_LDB(B1, 0, 1); PG8_SCHED; PG8_LDA(At, 0, 0); PG8_STAGE(PG8_SA(1, 1), a1 + hsA, voffA);
;             PG8_WAIT_V(8); PG8_WAIT_L(0); PG8_BAR; PG8_MMA(0, 0, At, B0); PG8_MMA(0, 1, At, B1); PG8_BAR; PG8_SCHED;
;             PG8_LDA(At, 0, 1); PG8_STAGE(PG8_SB(0, 0), b2, voffB); PG8_STAGE(PG8_SB(0, 1), b2 + hsB, voffB); PG8_STAGE(PG8_SA(0, 0), a2, voffA);
;             PG8_WAIT_V(8); PG8_WAIT_L(0); PG8_BAR; PG8_MMA(1, 0, At, B0); PG8_MMA(1, 1, At, B1); PG8_BAR; PG8_SCHED;
.LBB0_1350:
	ds_read_b128 v[144:147], v155
	ds_read_b128 v[148:151], v155 offset:1024
	ds_read_b128 v[162:165], v155 offset:2048
	ds_read_b128 v[166:169], v155 offset:3072
	ds_read_b128 v[170:173], v156
	ds_read_b128 v[174:177], v156 offset:1024
	ds_read_b128 v[184:187], v156 offset:2048
	ds_read_b128 v[188:191], v156 offset:3072
	s_add_u32 s40, s38, 0xfffc0080
	s_addc_u32 s41, s39, -1
	s_cmp_eq_u32 s48, 12
	s_cselect_b32 s43, s25, s41
	s_cselect_b32 s42, s44, s40
	s_cselect_b32 s41, s15, s47
	s_cselect_b32 s40, s45, s46
	s_add_i32 m0, s17, 0xc000
	ds_read_b128 v[192:195], v157
	ds_read_b128 v[196:199], v157 offset:1024
	ds_read_b128 v[200:203], v157 offset:2048
	ds_read_b128 v[204:207], v157 offset:3072
	ds_read_b128 v[208:211], v157 offset:4096
	ds_read_b128 v[212:215], v157 offset:5120
	ds_read_b128 v[216:219], v157 offset:6144
	ds_read_b128 v[220:223], v157 offset:7168
	global_load_lds_dwordx4 v136, s[38:39]
	s_add_i32 m0, s17, 0xe000
	s_nop 0
	global_load_lds_dwordx4 v138, s[38:39]
	s_waitcnt vmcnt(8)
	s_waitcnt lgkmcnt(0)
	s_barrier
	s_setprio 1
	s_waitcnt lgkmcnt(0)
	v_mfma_f32_16x16x32_bf16 v[124:127], v[144:147], v[192:195], v[124:127]
	v_mfma_f32_16x16x32_bf16 v[120:123], v[162:165], v[192:195], v[120:123]
	v_mfma_f32_16x16x32_bf16 v[108:111], v[144:147], v[200:203], v[108:111]
	v_mfma_f32_16x16x32_bf16 v[104:107], v[162:165], v[200:203], v[104:107]
	v_mfma_f32_16x16x32_bf16 v[92:95], v[144:147], v[208:211], v[92:95]
	v_mfma_f32_16x16x32_bf16 v[88:91], v[162:165], v[208:211], v[88:91]
	v_mfma_f32_16x16x32_bf16 v[76:79], v[144:147], v[216:219], v[76:79]
	v_mfma_f32_16x16x32_bf16 v[72:75], v[162:165], v[216:219], v[72:75]
	v_mfma_f32_16x16x32_bf16 v[124:127], v[148:151], v[196:199], v[124:127]
	v_mfma_f32_16x16x32_bf16 v[120:123], v[166:169], v[196:199], v[120:123]
	v_mfma_f32_16x16x32_bf16 v[108:111], v[148:151], v[204:207], v[108:111]
	v_mfma_f32_16x16x32_bf16 v[104:107], v[166:169], v[204:207], v[104:107]
	v_mfma_f32_16x16x32_bf16 v[92:95], v[148:151], v[212:215], v[92:95]
	v_mfma_f32_16x16x32_bf16 v[88:91], v[166:169], v[212:215], v[88:91]
	v_mfma_f32_16x16x32_bf16 v[76:79], v[148:151], v[220:223], v[76:79]
	v_mfma_f32_16x16x32_bf16 v[72:75], v[166:169], v[220:223], v[72:75]
	s_setprio 0
	s_setprio 1
	v_mfma_f32_16x16x32_bf16 v[116:119], v[170:173], v[192:195], v[116:119]
	v_mfma_f32_16x16x32_bf16 v[112:115], v[184:187], v[192:195], v[112:115]
	v_mfma_f32_16x16x32_bf16 v[100:103], v[170:173], v[200:203], v[100:103]
	v_mfma_f32_16x16x32_bf16 v[96:99], v[184:187], v[200:203], v[96:99]
	v_mfma_f32_16x16x32_bf16 v[84:87], v[170:173], v[208:211], v[84:87]
	v_mfma_f32_16x16x32_bf16 v[80:83], v[184:187], v[208:211], v[80:83]
	v_mfma_f32_16x16x32_bf16 v[68:71], v[170:173], v[216:219], v[68:71]
	v_mfma_f32_16x16x32_bf16 v[64:67], v[184:187], v[216:219], v[64:67]
	v_mfma_f32_16x16x32_bf16 v[116:119], v[174:177], v[196:199], v[116:119]
	v_mfma_f32_16x16x32_bf16 v[112:115], v[188:191], v[196:199], v[112:115]
	v_mfma_f32_16x16x32_bf16 v[100:103], v[174:177], v[204:207], v[100:103]
	v_mfma_f32_16x16x32_bf16 v[96:99], v[188:191], v[204:207], v[96:99]
	v_mfma_f32_16x16x32_bf16 v[84:87], v[174:177], v[212:215], v[84:87]
	v_mfma_f32_16x16x32_bf16 v[80:83], v[188:191], v[212:215], v[80:83]
	v_mfma_f32_16x16x32_bf16 v[68:71], v[174:177], v[220:223], v[68:71]
	v_mfma_f32_16x16x32_bf16 v[64:67], v[188:191], v[220:223], v[64:67]
	s_setprio 0
	s_barrier
	s_add_i32 s49, s30, s4
	s_mov_b32 m0, s49
	ds_read_b128 v[192:195], v157 offset:16384
	ds_read_b128 v[196:199], v157 offset:17408
	ds_read_b128 v[200:203], v157 offset:18432
	ds_read_b128 v[204:207], v157 offset:19456
	ds_read_b128 v[208:211], v157 offset:20480
	ds_read_b128 v[212:215], v157 offset:21504
	ds_read_b128 v[216:219], v157 offset:22528
	ds_read_b128 v[220:223], v157 offset:23552
	global_load_lds_dwordx4 v132, s[40:41]
	s_add_i32 m0, s49, 0x2000
	s_add_u32 s50, s40, 0x40000
	s_addc_u32 s51, s41, 0
	s_add_i32 s49, s31, s4
	global_load_lds_dwordx4 v128, s[40:41]
	s_mov_b32 m0, s49
	s_nop 0
	global_load_lds_dwordx4 v132, s[50:51]
	s_add_i32 m0, s49, 0x2000
	s_nop 0
	global_load_lds_dwordx4 v128, s[50:51]
	s_mov_b32 m0, s17
	s_nop 0
	global_load_lds_dwordx4 v134, s[42:43]
	s_mov_b32 m0, s18
	s_nop 0
	global_load_lds_dwordx4 v130, s[42:43]
	s_waitcnt vmcnt(8)
	s_waitcnt lgkmcnt(0)
	s_barrier
	s_setprio 1
	s_waitcnt lgkmcnt(0)
	v_mfma_f32_16x16x32_bf16 v[60:63], v[144:147], v[192:195], v[60:63]
	v_mfma_f32_16x16x32_bf16 v[56:59], v[162:165], v[192:195], v[56:59]
	v_mfma_f32_16x16x32_bf16 v[44:47], v[144:147], v[200:203], v[44:47]
	v_mfma_f32_16x16x32_bf16 v[40:43], v[162:165], v[200:203], v[40:43]
	v_mfma_f32_16x16x32_bf16 v[28:31], v[144:147], v[208:211], v[28:31]
	v_mfma_f32_16x16x32_bf16 v[24:27], v[162:165], v[208:211], v[24:27]
	v_mfma_f32_16x16x32_bf16 v[12:15], v[144:147], v[216:219], v[12:15]
	v_mfma_f32_16x16x32_bf16 v[8:11], v[162:165], v[216:219], v[8:11]
	v_mfma_f32_16x16x32_bf16 v[60:63], v[148:151], v[196:199], v[60:63]
	v_mfma_f32_16x16x32_bf16 v[56:59], v[166:169], v[196:199], v[56:59]
	v_mfma_f32_16x16x32_bf16 v[44:47], v[148:151], v[204:207], v[44:47]
	v_mfma_f32_16x16x32_bf16 v[40:43], v[166:169], v[204:207], v[40:43]
	v_mfma_f32_16x16x32_bf16 v[28:31], v[148:151], v[212:215], v[28:31]
	v_mfma_f32_16x16x32_bf16 v[24:27], v[166:169], v[212:215], v[24:27]
	v_mfma_f32_16x16x32_bf16 v[12:15], v[148:151], v[220:223], v[12:15]
	v_mfma_f32_16x16x32_bf16 v[8:11], v[166:169], v[220:223], v[8:11]
	s_setprio 0
	s_setprio 1
	v_mfma_f32_16x16x32_bf16 v[52:55], v[170:173], v[192:195], v[52:55]
	v_mfma_f32_16x16x32_bf16 v[48:51], v[184:187], v[192:195], v[48:51]
	v_mfma_f32_16x16x32_bf16 v[36:39], v[170:173], v[200:203], v[36:39]
	v_mfma_f32_16x16x32_bf16 v[32:35], v[184:187], v[200:203], v[32:35]
	v_mfma_f32_16x16x32_bf16 v[20:23], v[170:173], v[208:211], v[20:23]
	v_mfma_f32_16x16x32_bf16 v[16:19], v[184:187], v[208:211], v[16:19]
	v_mfma_f32_16x16x32_bf16 v[4:7], v[170:173], v[216:219], v[4:7]
	v_mfma_f32_16x16x32_bf16 v[0:3], v[184:187], v[216:219], v[0:3]
	v_mfma_f32_16x16x32_bf16 v[52:55], v[174:177], v[196:199], v[52:55]
	v_mfma_f32_16x16x32_bf16 v[48:51], v[188:191], v[196:199], v[48:51]
	v_mfma_f32_16x16x32_bf16 v[36:39], v[174:177], v[204:207], v[36:39]
	v_mfma_f32_16x16x32_bf16 v[32:35], v[188:191], v[204:207], v[32:35]
	v_mfma_f32_16x16x32_bf16 v[20:23], v[174:177], v[212:215], v[20:23]
	v_mfma_f32_16x16x32_bf16 v[16:19], v[188:191], v[212:215], v[16:19]
	v_mfma_f32_16x16x32_bf16 v[4:7], v[174:177], v[220:223], v[4:7]
	v_mfma_f32_16x16x32_bf16 v[0:3], v[188:191], v[220:223], v[0:3]
	s_setprio 0
	s_barrier
; #define PG8_STAGE(bufoff, gbase, voff) do { _Pragma("unroll") for (int _i = 0; _i < 2; ++_i) \
;         __builtin_amdgcn_global_load_lds((const unsigned*)((const char*)(gbase) + (voff)[_i]), (LAS unsigned*)(lds + (bufoff) + ldsw + _i * 8192), 16, 0, 0); } while (0)
; #define PG8_LDA(dst, b, h) do { _Pragma("unroll") for (int m = 0; m < 4; ++m) _Pragma("unroll") for (int k = 0; k < 2; ++k) dst[m][k] = *(const LAS bf16x8*)(lds + PG8_SA(b, h) + aoff + m * 2048 + k * 1024); } while (0)
; #define PG8_LDB(dst, b, h) do { _Pragma("unroll") for (int n = 0; n < 2; ++n) _Pragma("unroll") for (int k = 0; k < 2; ++k) dst[n][k] = *(const LAS bf16x8*)(lds + PG8_SB(b, h) + boff + n * 2048 + k * 1024); } while (0)
; #define PG8_MMA(ai, bj, At, Bt) do { __builtin_amdgcn_s_setprio(1); _Pragma("unroll") for (int m = 0; m < 4; ++m) _Pragma("unroll") for (int n = 0; n < 2; ++n) _Pragma("unroll") for (int k = 0; k < 2; ++k) \
;         acc[ai][bj][m][n] = __builtin_amdgcn_mfma_f32_16x16x32_bf16(Bt[n][k], At[m][k], acc[ai][bj][m][n], 0, 0, 0); __builtin_amdgcn_s_setprio(0); } while (0)
; #define PG8_WAIT_V(n) asm volatile("s_waitcnt vmcnt(" #n ")" ::: "memory")
; #define PG8_WAIT_L(n) asm volatile("s_waitcnt lgkmcnt(" #n ")" ::: "memory")
; #define PG8_BAR __builtin_amdgcn_s_barrier()
; #define PG8_SCHED __builtin_amdgcn_sched_barrier(0)
; template <class Epi>
; __device__ __forceinline__ void gemm_phase(LAS unsigned char* lds, const Gemm g, const StaticOrder& S, const Epi& E) {
;     ...
;             PG8_LDB(B0, 1, 0); PG8_LDB(B1, 1, 1); PG8_SCHED; PG8_LDA(At, 1, 0); PG8_STAGE(PG8_SA(0, 1), a2 + hsA, voffA);
;             PG8_WAIT_V(8); PG8_WAIT_L(0); PG8_BAR; PG8_MMA(0, 0, At, B0); PG8_MMA(0, 1, At, B1); PG8_BAR; PG8_SCHED;
;             PG8_LDA(At, 1, 1); PG8_STAGE(PG8_SB(1, 0), b3, voffB); PG8_STAGE(PG8_SB(1, 1), b3 + hsB, voffB); PG8_STAGE(PG8_SA(1, 0), a3, voffA);
;             PG8_WAIT_V(8); PG8_WAIT_L(0); PG8_BAR; PG8_MMA(1, 0, At, B0); PG8_MMA(1, 1, At, B1); PG8_BAR; PG8_SCHED;
;         }
	s_add_i32 s49, 0, 0x18000
	v_add_u32_e32 v159, s49, v153
	s_add_i32 s50, 0, 0x1c000
	ds_read_b128 v[144:147], v159
	ds_read_b128 v[148:151], v159 offset:1024
	ds_read_b128 v[162:165], v159 offset:2048
	ds_read_b128 v[166:169], v159 offset:3072
	v_add_u32_e32 v159, s50, v153
	ds_read_b128 v[170:173], v159
	ds_read_b128 v[174:177], v159 offset:1024
	ds_read_b128 v[184:187], v159 offset:2048
	ds_read_b128 v[188:191], v159 offset:3072
	s_add_u32 s42, s42, 0x40000
	s_addc_u32 s43, s43, 0
	s_mov_b32 m0, s19
	ds_read_b128 v[192:195], v157 offset:32768
	ds_read_b128 v[196:199], v157 offset:33792
	ds_read_b128 v[200:203], v157 offset:34816
	ds_read_b128 v[204:207], v157 offset:35840
	ds_read_b128 v[208:211], v157 offset:36864
	ds_read_b128 v[212:215], v157 offset:37888
	ds_read_b128 v[216:219], v157 offset:38912
	ds_read_b128 v[220:223], v157 offset:39936
	global_load_lds_dwordx4 v134, s[42:43]
	s_mov_b32 m0, s22
	s_nop 0
	global_load_lds_dwordx4 v130, s[42:43]
	s_waitcnt vmcnt(8)
	s_waitcnt lgkmcnt(0)
	s_barrier
	s_setprio 1
	s_waitcnt lgkmcnt(0)
	v_mfma_f32_16x16x32_bf16 v[124:127], v[144:147], v[192:195], v[124:127]
	v_mfma_f32_16x16x32_bf16 v[120:123], v[162:165], v[192:195], v[120:123]
	v_mfma_f32_16x16x32_bf16 v[108:111], v[144:147], v[200:203], v[108:111]
	v_mfma_f32_16x16x32_bf16 v[104:107], v[162:165], v[200:203], v[104:107]
	v_mfma_f32_16x16x32_bf16 v[92:95], v[144:147], v[208:211], v[92:95]
	v_mfma_f32_16x16x32_bf16 v[88:91], v[162:165], v[208:211], v[88:91]
	v_mfma_f32_16x16x32_bf16 v[76:79], v[144:147], v[216:219], v[76:79]
	v_mfma_f32_16x16x32_bf16 v[72:75], v[162:165], v[216:219], v[72:75]
	v_mfma_f32_16x16x32_bf16 v[124:127], v[148:151], v[196:199], v[124:127]
	v_mfma_f32_16x16x32_bf16 v[120:123], v[166:169], v[196:199], v[120:123]
	v_mfma_f32_16x16x32_bf16 v[108:111], v[148:151], v[204:207], v[108:111]
	v_mfma_f32_16x16x32_bf16 v[104:107], v[166:169], v[204:207], v[104:107]
	v_mfma_f32_16x16x32_bf16 v[92:95], v[148:151], v[212:215], v[92:95]
	v_mfma_f32_16x16x32_bf16 v[88:91], v[166:169], v[212:215], v[88:91]
	v_mfma_f32_16x16x32_bf16 v[76:79], v[148:151], v[220:223], v[76:79]
	v_mfma_f32_16x16x32_bf16 v[72:75], v[166:169], v[220:223], v[72:75]
	s_setprio 0
	s_setprio 1
	v_mfma_f32_16x16x32_bf16 v[116:119], v[170:173], v[192:195], v[116:119]
	v_mfma_f32_16x16x32_bf16 v[112:115], v[184:187], v[192:195], v[112:115]
	v_mfma_f32_16x16x32_bf16 v[100:103], v[170:173], v[200:203], v[100:103]
	v_mfma_f32_16x16x32_bf16 v[96:99], v[184:187], v[200:203], v[96:99]
	v_mfma_f32_16x16x32_bf16 v[84:87], v[170:173], v[208:211], v[84:87]
	v_mfma_f32_16x16x32_bf16 v[80:83], v[184:187], v[208:211], v[80:83]
	v_mfma_f32_16x16x32_bf16 v[68:71], v[170:173], v[216:219], v[68:71]
	v_mfma_f32_16x16x32_bf16 v[64:67], v[184:187], v[216:219], v[64:67]
	v_mfma_f32_16x16x32_bf16 v[116:119], v[174:177], v[196:199], v[116:119]
	v_mfma_f32_16x16x32_bf16 v[112:115], v[188:191], v[196:199], v[112:115]
	v_mfma_f32_16x16x32_bf16 v[100:103], v[174:177], v[204:207], v[100:103]
	v_mfma_f32_16x16x32_bf16 v[96:99], v[188:191], v[204:207], v[96:99]
	v_mfma_f32_16x16x32_bf16 v[84:87], v[174:177], v[212:215], v[84:87]
	v_mfma_f32_16x16x32_bf16 v[80:83], v[188:191], v[212:215], v[80:83]
	v_mfma_f32_16x16x32_bf16 v[68:71], v[174:177], v[220:223], v[68:71]
	v_mfma_f32_16x16x32_bf16 v[64:67], v[188:191], v[220:223], v[64:67]
	s_setprio 0
	s_barrier
	s_add_u32 s98, s40, 0x80
	s_addc_u32 s99, s41, 0
	s_add_u32 s100, s42, 0xfffc0080
	s_addc_u32 s101, s43, -1
	s_add_i32 s42, s49, s4
	s_mov_b32 m0, s42
	ds_read_b128 v[192:195], v157 offset:49152
	ds_read_b128 v[196:199], v157 offset:50176
	ds_read_b128 v[200:203], v157 offset:51200
	ds_read_b128 v[204:207], v157 offset:52224
	ds_read_b128 v[208:211], v157 offset:53248
	ds_read_b128 v[212:215], v157 offset:54272
	ds_read_b128 v[216:219], v157 offset:55296
	ds_read_b128 v[220:223], v157 offset:56320
	global_load_lds_dwordx4 v132, s[98:99]
	s_add_i32 m0, s42, 0x2000
	s_add_u32 s40, s40, 0x40080
	s_addc_u32 s41, s41, 0
	s_add_i32 s42, s50, s4
	global_load_lds_dwordx4 v128, s[98:99]
	s_mov_b32 m0, s42
	s_nop 0
	global_load_lds_dwordx4 v132, s[40:41]
	s_add_i32 m0, s42, 0x2000
	s_nop 0
	global_load_lds_dwordx4 v128, s[40:41]
	s_mov_b32 m0, s0
	s_nop 0
	global_load_lds_dwordx4 v134, s[100:101]
	s_mov_b32 m0, s1
	s_nop 0
	global_load_lds_dwordx4 v130, s[100:101]
	s_waitcnt vmcnt(8)
	s_waitcnt lgkmcnt(0)
	s_barrier
	s_setprio 1
	s_waitcnt lgkmcnt(0)
	v_mfma_f32_16x16x32_bf16 v[60:63], v[144:147], v[192:195], v[60:63]
	v_mfma_f32_16x16x32_bf16 v[56:59], v[162:165], v[192:195], v[56:59]
	v_mfma_f32_16x16x32_bf16 v[44:47], v[144:147], v[200:203], v[44:47]
	v_mfma_f32_16x16x32_bf16 v[40:43], v[162:165], v[200:203], v[40:43]
	v_mfma_f32_16x16x32_bf16 v[28:31], v[144:147], v[208:211], v[28:31]
	v_mfma_f32_16x16x32_bf16 v[24:27], v[162:165], v[208:211], v[24:27]
	v_mfma_f32_16x16x32_bf16 v[12:15], v[144:147], v[216:219], v[12:15]
	v_mfma_f32_16x16x32_bf16 v[8:11], v[162:165], v[216:219], v[8:11]
	v_mfma_f32_16x16x32_bf16 v[60:63], v[148:151], v[196:199], v[60:63]
	v_mfma_f32_16x16x32_bf16 v[56:59], v[166:169], v[196:199], v[56:59]
	v_mfma_f32_16x16x32_bf16 v[44:47], v[148:151], v[204:207], v[44:47]
	v_mfma_f32_16x16x32_bf16 v[40:43], v[166:169], v[204:207], v[40:43]
	v_mfma_f32_16x16x32_bf16 v[28:31], v[148:151], v[212:215], v[28:31]
	v_mfma_f32_16x16x32_bf16 v[24:27], v[166:169], v[212:215], v[24:27]
	v_mfma_f32_16x16x32_bf16 v[12:15], v[148:151], v[220:223], v[12:15]
	v_mfma_f32_16x16x32_bf16 v[8:11], v[166:169], v[220:223], v[8:11]
	s_setprio 0
	s_setprio 1
	v_mfma_f32_16x16x32_bf16 v[52:55], v[170:173], v[192:195], v[52:55]
	v_mfma_f32_16x16x32_bf16 v[48:51], v[184:187], v[192:195], v[48:51]
	v_mfma_f32_16x16x32_bf16 v[36:39], v[170:173], v[200:203], v[36:39]
	v_mfma_f32_16x16x32_bf16 v[32:35], v[184:187], v[200:203], v[32:35]
	v_mfma_f32_16x16x32_bf16 v[20:23], v[170:173], v[208:211], v[20:23]
	v_mfma_f32_16x16x32_bf16 v[16:19], v[184:187], v[208:211], v[16:19]
	v_mfma_f32_16x16x32_bf16 v[4:7], v[170:173], v[216:219], v[4:7]
	v_mfma_f32_16x16x32_bf16 v[0:3], v[184:187], v[216:219], v[0:3]
	v_mfma_f32_16x16x32_bf16 v[52:55], v[174:177], v[196:199], v[52:55]
	v_mfma_f32_16x16x32_bf16 v[48:51], v[188:191], v[196:199], v[48:51]
	v_mfma_f32_16x16x32_bf16 v[36:39], v[174:177], v[204:207], v[36:39]
	v_mfma_f32_16x16x32_bf16 v[32:35], v[188:191], v[204:207], v[32:35]
	v_mfma_f32_16x16x32_bf16 v[20:23], v[174:177], v[212:215], v[20:23]
	v_mfma_f32_16x16x32_bf16 v[16:19], v[188:191], v[212:215], v[16:19]
	v_mfma_f32_16x16x32_bf16 v[4:7], v[174:177], v[220:223], v[4:7]
	v_mfma_f32_16x16x32_bf16 v[0:3], v[188:191], v[220:223], v[0:3]
	s_add_i32 s48, s48, 2
	s_add_u32 s38, s38, 0x100
	s_addc_u32 s39, s39, 0
	s_add_u32 s46, s46, 0x100
	s_addc_u32 s47, s47, 0
	s_cmp_gt_u32 s48, 13
	s_setprio 0
	s_barrier
	s_cbranch_scc0 .LBB0_1350
	s_and_b64 vcc, exec, s[12:13]
	s_cbranch_vccz .LBB0_1353
	s_barrier

; #define PG8_STAGE(bufoff, gbase, voff) do { _Pragma("unroll") for (int _i = 0; _i < 2; ++_i) \
;         __builtin_amdgcn_global_load_lds((const unsigned*)((const char*)(gbase) + (voff)[_i]), (LAS unsigned*)(lds + (bufoff) + ldsw + _i * 8192), 16, 0, 0); } while (0)
; #define PG8_LDA(dst, b, h) do { _Pragma("unroll") for (int m = 0; m < 4; ++m) _Pragma("unroll") for (int k = 0; k < 2; ++k) dst[m][k] = *(const LAS bf16x8*)(lds + PG8_SA(b, h) + aoff + m * 2048 + k * 1024); } while (0)
; #define PG8_LDB(dst, b, h) do { _Pragma("unroll") for (int n = 0; n < 2; ++n) _Pragma("unroll") for (int k = 0; k < 2; ++k) dst[n][k] = *(const LAS bf16x8*)(lds + PG8_SB(b, h) + boff + n * 2048 + k * 1024); } while (0)
; #define PG8_MMA(ai, bj, At, Bt) do { __builtin_amdgcn_s_setprio(1); _Pragma("unroll") for (int m = 0; m < 4; ++m) _Pragma("unroll") for (int n = 0; n < 2; ++n) _Pragma("unroll") for (int k = 0; k < 2; ++k) \
;         acc[ai][bj][m][n] = __builtin_amdgcn_mfma_f32_16x16x32_bf16(Bt[n][k], At[m][k], acc[ai][bj][m][n], 0, 0, 0); __builtin_amdgcn_s_setprio(0); } while (0)
; #define PG8_WAIT_V(n) asm volatile("s_waitcnt vmcnt(" #n ")" ::: "memory")
; #define PG8_WAIT_L(n) asm volatile("s_waitcnt lgkmcnt(" #n ")" ::: "memory")
; #define PG8_BAR __builtin_amdgcn_s_barrier()
; #define PG8_SCHED __builtin_amdgcn_sched_barrier(0)
; template <class Epi>
; __device__ __forceinline__ void gemm_phase(LAS unsigned char* lds, const Gemm g, const StaticOrder& S, const Epi& E) {
;     ...
;             PG8_LDB(B0, 0, 0); PG8_LDB(B1, 0, 1); PG8_SCHED; PG8_LDA(At, 0, 0); PG8_STAGE(PG8_SA(1, 1), a1 + hsA, voffA);
;             PG8_WAIT_V(8); PG8_WAIT_L(0); PG8_BAR; PG8_MMA(0, 0, At, B0); PG8_MMA(0, 1, At, B1); PG8_BAR; PG8_SCHED;
;             PG8_LDA(At, 0, 1); PG8_STAGE(PG8_SB(0, 0), b2, voffB); PG8_STAGE(PG8_SB(0, 1), b2 + hsB, voffB); PG8_STAGE(PG8_SA(0, 0), a2, voffA);
;             PG8_WAIT_V(8); PG8_WAIT_L(0); PG8_BAR; PG8_MMA(1, 0, At, B0); PG8_MMA(1, 1, At, B1); PG8_BAR; PG8_SCHED;
.LBB0_1433:
	ds_read_b128 v[144:147], v202
	ds_read_b128 v[148:151], v202 offset:1024
	ds_read_b128 v[152:155], v202 offset:2048
	ds_read_b128 v[156:159], v202 offset:3072
	ds_read_b128 v[160:163], v203
	ds_read_b128 v[164:167], v203 offset:1024
	ds_read_b128 v[168:171], v203 offset:2048
	ds_read_b128 v[172:175], v203 offset:3072
	s_add_u32 s34, s26, 0x100
	s_addc_u32 s35, s27, 0
	s_cmp_eq_u32 s51, 40
	s_cselect_b32 s39, s1, s35
	s_cselect_b32 s38, s0, s34
	s_cselect_b32 s37, s23, s50
	s_cselect_b32 s36, s22, s25
	s_add_i32 m0, s17, 0xc000
	ds_read_b128 v[216:219], v204
	ds_read_b128 v[220:223], v204 offset:1024
	ds_read_b128 v[224:227], v204 offset:2048
	ds_read_b128 v[228:231], v204 offset:3072
	ds_read_b128 v[232:235], v204 offset:4096
	ds_read_b128 v[236:239], v204 offset:5120
	ds_read_b128 v[240:243], v204 offset:6144
	ds_read_b128 v[244:247], v204 offset:7168
	global_load_lds_dwordx4 v136, s[26:27]
	s_add_i32 m0, s17, 0xe000
	s_nop 0
	global_load_lds_dwordx4 v138, s[26:27]
	s_waitcnt vmcnt(8)
	s_waitcnt lgkmcnt(0)
	s_barrier
	s_setprio 1
	s_waitcnt lgkmcnt(0)
	v_mfma_f32_16x16x32_bf16 v[124:127], v[144:147], v[216:219], v[124:127]
	v_mfma_f32_16x16x32_bf16 v[120:123], v[152:155], v[216:219], v[120:123]
	v_mfma_f32_16x16x32_bf16 v[108:111], v[144:147], v[224:227], v[108:111]
	v_mfma_f32_16x16x32_bf16 v[104:107], v[152:155], v[224:227], v[104:107]
	v_mfma_f32_16x16x32_bf16 v[92:95], v[144:147], v[232:235], v[92:95]
	v_mfma_f32_16x16x32_bf16 v[88:91], v[152:155], v[232:235], v[88:91]
	v_mfma_f32_16x16x32_bf16 v[76:79], v[144:147], v[240:243], v[76:79]
	v_mfma_f32_16x16x32_bf16 v[72:75], v[152:155], v[240:243], v[72:75]
	v_mfma_f32_16x16x32_bf16 v[124:127], v[148:151], v[220:223], v[124:127]
	v_mfma_f32_16x16x32_bf16 v[120:123], v[156:159], v[220:223], v[120:123]
	v_mfma_f32_16x16x32_bf16 v[108:111], v[148:151], v[228:231], v[108:111]
	v_mfma_f32_16x16x32_bf16 v[104:107], v[156:159], v[228:231], v[104:107]
	v_mfma_f32_16x16x32_bf16 v[92:95], v[148:151], v[236:239], v[92:95]
	v_mfma_f32_16x16x32_bf16 v[88:91], v[156:159], v[236:239], v[88:91]
	v_mfma_f32_16x16x32_bf16 v[76:79], v[148:151], v[244:247], v[76:79]
	v_mfma_f32_16x16x32_bf16 v[72:75], v[156:159], v[244:247], v[72:75]
	s_setprio 0
	s_setprio 1
	v_mfma_f32_16x16x32_bf16 v[116:119], v[160:163], v[216:219], v[116:119]
	v_mfma_f32_16x16x32_bf16 v[112:115], v[168:171], v[216:219], v[112:115]
	v_mfma_f32_16x16x32_bf16 v[100:103], v[160:163], v[224:227], v[100:103]
	v_mfma_f32_16x16x32_bf16 v[96:99], v[168:171], v[224:227], v[96:99]
	v_mfma_f32_16x16x32_bf16 v[84:87], v[160:163], v[232:235], v[84:87]
	v_mfma_f32_16x16x32_bf16 v[80:83], v[168:171], v[232:235], v[80:83]
	v_mfma_f32_16x16x32_bf16 v[68:71], v[160:163], v[240:243], v[68:71]
	v_mfma_f32_16x16x32_bf16 v[64:67], v[168:171], v[240:243], v[64:67]
	v_mfma_f32_16x16x32_bf16 v[116:119], v[164:167], v[220:223], v[116:119]
	v_mfma_f32_16x16x32_bf16 v[112:115], v[172:175], v[220:223], v[112:115]
	v_mfma_f32_16x16x32_bf16 v[100:103], v[164:167], v[228:231], v[100:103]
	v_mfma_f32_16x16x32_bf16 v[96:99], v[172:175], v[228:231], v[96:99]
	v_mfma_f32_16x16x32_bf16 v[84:87], v[164:167], v[236:239], v[84:87]
	v_mfma_f32_16x16x32_bf16 v[80:83], v[172:175], v[236:239], v[80:83]
	v_mfma_f32_16x16x32_bf16 v[68:71], v[164:167], v[244:247], v[68:71]
	v_mfma_f32_16x16x32_bf16 v[64:67], v[172:175], v[244:247], v[64:67]
	s_setprio 0
	s_barrier
	s_add_i32 s26, s45, s16
	s_mov_b32 m0, s26
	ds_read_b128 v[216:219], v204 offset:16384
	ds_read_b128 v[220:223], v204 offset:17408
	ds_read_b128 v[224:227], v204 offset:18432
	ds_read_b128 v[228:231], v204 offset:19456
	ds_read_b128 v[232:235], v204 offset:20480
	ds_read_b128 v[236:239], v204 offset:21504
	ds_read_b128 v[240:243], v204 offset:22528
	ds_read_b128 v[244:247], v204 offset:23552
	global_load_lds_dwordx4 v130, s[36:37]
	s_add_i32 m0, s26, 0x2000
	s_add_u32 s26, s36, 0xb0000
	s_addc_u32 s27, s37, 0
	s_add_i32 s52, s46, s16
	global_load_lds_dwordx4 v134, s[36:37]
	s_mov_b32 m0, s52
	s_nop 0
	global_load_lds_dwordx4 v130, s[26:27]
	s_add_i32 m0, s52, 0x2000
	s_nop 0
	global_load_lds_dwordx4 v134, s[26:27]
	s_mov_b32 m0, s17
	s_nop 0
	global_load_lds_dwordx4 v128, s[38:39]
	s_mov_b32 m0, s28
	s_nop 0
	global_load_lds_dwordx4 v132, s[38:39]
	s_waitcnt vmcnt(8)
	s_waitcnt lgkmcnt(0)
	s_barrier
	s_setprio 1
	s_waitcnt lgkmcnt(0)
	v_mfma_f32_16x16x32_bf16 v[60:63], v[144:147], v[216:219], v[60:63]
	v_mfma_f32_16x16x32_bf16 v[56:59], v[152:155], v[216:219], v[56:59]
	v_mfma_f32_16x16x32_bf16 v[44:47], v[144:147], v[224:227], v[44:47]
	v_mfma_f32_16x16x32_bf16 v[40:43], v[152:155], v[224:227], v[40:43]
	v_mfma_f32_16x16x32_bf16 v[28:31], v[144:147], v[232:235], v[28:31]
	v_mfma_f32_16x16x32_bf16 v[24:27], v[152:155], v[232:235], v[24:27]
	v_mfma_f32_16x16x32_bf16 v[12:15], v[144:147], v[240:243], v[12:15]
	v_mfma_f32_16x16x32_bf16 v[8:11], v[152:155], v[240:243], v[8:11]
	v_mfma_f32_16x16x32_bf16 v[60:63], v[148:151], v[220:223], v[60:63]
	v_mfma_f32_16x16x32_bf16 v[56:59], v[156:159], v[220:223], v[56:59]
	v_mfma_f32_16x16x32_bf16 v[44:47], v[148:151], v[228:231], v[44:47]
	v_mfma_f32_16x16x32_bf16 v[40:43], v[156:159], v[228:231], v[40:43]
	v_mfma_f32_16x16x32_bf16 v[28:31], v[148:151], v[236:239], v[28:31]
	v_mfma_f32_16x16x32_bf16 v[24:27], v[156:159], v[236:239], v[24:27]
	v_mfma_f32_16x16x32_bf16 v[12:15], v[148:151], v[244:247], v[12:15]
	v_mfma_f32_16x16x32_bf16 v[8:11], v[156:159], v[244:247], v[8:11]
	s_setprio 0
	s_setprio 1
	v_mfma_f32_16x16x32_bf16 v[52:55], v[160:163], v[216:219], v[52:55]
	v_mfma_f32_16x16x32_bf16 v[48:51], v[168:171], v[216:219], v[48:51]
	v_mfma_f32_16x16x32_bf16 v[36:39], v[160:163], v[224:227], v[36:39]
	v_mfma_f32_16x16x32_bf16 v[32:35], v[168:171], v[224:227], v[32:35]
	v_mfma_f32_16x16x32_bf16 v[20:23], v[160:163], v[232:235], v[20:23]
	v_mfma_f32_16x16x32_bf16 v[16:19], v[168:171], v[232:235], v[16:19]
	v_mfma_f32_16x16x32_bf16 v[4:7], v[160:163], v[240:243], v[4:7]
	v_mfma_f32_16x16x32_bf16 v[0:3], v[168:171], v[240:243], v[0:3]
	v_mfma_f32_16x16x32_bf16 v[52:55], v[164:167], v[220:223], v[52:55]
	v_mfma_f32_16x16x32_bf16 v[48:51], v[172:175], v[220:223], v[48:51]
	v_mfma_f32_16x16x32_bf16 v[36:39], v[164:167], v[228:231], v[36:39]
	v_mfma_f32_16x16x32_bf16 v[32:35], v[172:175], v[228:231], v[32:35]
	v_mfma_f32_16x16x32_bf16 v[20:23], v[164:167], v[236:239], v[20:23]
	v_mfma_f32_16x16x32_bf16 v[16:19], v[172:175], v[236:239], v[16:19]
	v_mfma_f32_16x16x32_bf16 v[4:7], v[164:167], v[244:247], v[4:7]
	v_mfma_f32_16x16x32_bf16 v[0:3], v[172:175], v[244:247], v[0:3]
	s_setprio 0
	s_barrier
; #define PG8_STAGE(bufoff, gbase, voff) do { _Pragma("unroll") for (int _i = 0; _i < 2; ++_i) \
;         __builtin_amdgcn_global_load_lds((const unsigned*)((const char*)(gbase) + (voff)[_i]), (LAS unsigned*)(lds + (bufoff) + ldsw + _i * 8192), 16, 0, 0); } while (0)
; #define PG8_LDA(dst, b, h) do { _Pragma("unroll") for (int m = 0; m < 4; ++m) _Pragma("unroll") for (int k = 0; k < 2; ++k) dst[m][k] = *(const LAS bf16x8*)(lds + PG8_SA(b, h) + aoff + m * 2048 + k * 1024); } while (0)
; #define PG8_LDB(dst, b, h) do { _Pragma("unroll") for (int n = 0; n < 2; ++n) _Pragma("unroll") for (int k = 0; k < 2; ++k) dst[n][k] = *(const LAS bf16x8*)(lds + PG8_SB(b, h) + boff + n * 2048 + k * 1024); } while (0)
; #define PG8_MMA(ai, bj, At, Bt) do { __builtin_amdgcn_s_setprio(1); _Pragma("unroll") for (int m = 0; m < 4; ++m) _Pragma("unroll") for (int n = 0; n < 2; ++n) _Pragma("unroll") for (int k = 0; k < 2; ++k) \
;         acc[ai][bj][m][n] = __builtin_amdgcn_mfma_f32_16x16x32_bf16(Bt[n][k], At[m][k], acc[ai][bj][m][n], 0, 0, 0); __builtin_amdgcn_s_setprio(0); } while (0)
; #define PG8_WAIT_V(n) asm volatile("s_waitcnt vmcnt(" #n ")" ::: "memory")
; #define PG8_WAIT_L(n) asm volatile("s_waitcnt lgkmcnt(" #n ")" ::: "memory")
; #define PG8_BAR __builtin_amdgcn_s_barrier()
; #define PG8_SCHED __builtin_amdgcn_sched_barrier(0)
; template <class Epi>
; __device__ __forceinline__ void gemm_phase(LAS unsigned char* lds, const Gemm g, const StaticOrder& S, const Epi& E) {
;     ...
;             PG8_LDB(B0, 1, 0); PG8_LDB(B1, 1, 1); PG8_SCHED; PG8_LDA(At, 1, 0); PG8_STAGE(PG8_SA(0, 1), a2 + hsA, voffA);
;             PG8_WAIT_V(8); PG8_WAIT_L(0); PG8_BAR; PG8_MMA(0, 0, At, B0); PG8_MMA(0, 1, At, B1); PG8_BAR; PG8_SCHED;
;             PG8_LDA(At, 1, 1); PG8_STAGE(PG8_SB(1, 0), b3, voffB); PG8_STAGE(PG8_SB(1, 1), b3 + hsB, voffB); PG8_STAGE(PG8_SA(1, 0), a3, voffA);
;             PG8_WAIT_V(8); PG8_WAIT_L(0); PG8_BAR; PG8_MMA(1, 0, At, B0); PG8_MMA(1, 1, At, B1); PG8_BAR; PG8_SCHED;
;         }
	s_add_i32 s52, 0, 0x18000
	s_add_i32 s53, 0, 0x1c000
	v_add_u32_e32 v156, s52, v184
	v_add_u32_e32 v172, s53, v184
	ds_read_b128 v[144:147], v156
	ds_read_b128 v[148:151], v156 offset:1024
	ds_read_b128 v[152:155], v156 offset:2048
	ds_read_b128 v[156:159], v156 offset:3072
	ds_read_b128 v[160:163], v172
	ds_read_b128 v[164:167], v172 offset:1024
	ds_read_b128 v[168:171], v172 offset:2048
	ds_read_b128 v[172:175], v172 offset:3072
	s_add_u32 s26, s38, 0xb0000
	s_addc_u32 s27, s39, 0
	s_mov_b32 m0, s29
	ds_read_b128 v[216:219], v204 offset:32768
	ds_read_b128 v[220:223], v204 offset:33792
	ds_read_b128 v[224:227], v204 offset:34816
	ds_read_b128 v[228:231], v204 offset:35840
	ds_read_b128 v[232:235], v204 offset:36864
	ds_read_b128 v[236:239], v204 offset:37888
	ds_read_b128 v[240:243], v204 offset:38912
	ds_read_b128 v[244:247], v204 offset:39936
	global_load_lds_dwordx4 v128, s[26:27]
	s_mov_b32 m0, s30
	s_nop 0
	global_load_lds_dwordx4 v132, s[26:27]
	s_waitcnt vmcnt(8)
	s_waitcnt lgkmcnt(0)
	s_barrier
	s_setprio 1
	s_waitcnt lgkmcnt(0)
	v_mfma_f32_16x16x32_bf16 v[124:127], v[144:147], v[216:219], v[124:127]
	v_mfma_f32_16x16x32_bf16 v[120:123], v[152:155], v[216:219], v[120:123]
	v_mfma_f32_16x16x32_bf16 v[108:111], v[144:147], v[224:227], v[108:111]
	v_mfma_f32_16x16x32_bf16 v[104:107], v[152:155], v[224:227], v[104:107]
	v_mfma_f32_16x16x32_bf16 v[92:95], v[144:147], v[232:235], v[92:95]
	v_mfma_f32_16x16x32_bf16 v[88:91], v[152:155], v[232:235], v[88:91]
	v_mfma_f32_16x16x32_bf16 v[76:79], v[144:147], v[240:243], v[76:79]
	v_mfma_f32_16x16x32_bf16 v[72:75], v[152:155], v[240:243], v[72:75]
	v_mfma_f32_16x16x32_bf16 v[124:127], v[148:151], v[220:223], v[124:127]
	v_mfma_f32_16x16x32_bf16 v[120:123], v[156:159], v[220:223], v[120:123]
	v_mfma_f32_16x16x32_bf16 v[108:111], v[148:151], v[228:231], v[108:111]
	v_mfma_f32_16x16x32_bf16 v[104:107], v[156:159], v[228:231], v[104:107]
	v_mfma_f32_16x16x32_bf16 v[92:95], v[148:151], v[236:239], v[92:95]
	v_mfma_f32_16x16x32_bf16 v[88:91], v[156:159], v[236:239], v[88:91]
	v_mfma_f32_16x16x32_bf16 v[76:79], v[148:151], v[244:247], v[76:79]
	v_mfma_f32_16x16x32_bf16 v[72:75], v[156:159], v[244:247], v[72:75]
	s_setprio 0
	s_setprio 1
	v_mfma_f32_16x16x32_bf16 v[116:119], v[160:163], v[216:219], v[116:119]
	v_mfma_f32_16x16x32_bf16 v[112:115], v[168:171], v[216:219], v[112:115]
	v_mfma_f32_16x16x32_bf16 v[100:103], v[160:163], v[224:227], v[100:103]
	v_mfma_f32_16x16x32_bf16 v[96:99], v[168:171], v[224:227], v[96:99]
	v_mfma_f32_16x16x32_bf16 v[84:87], v[160:163], v[232:235], v[84:87]
	v_mfma_f32_16x16x32_bf16 v[80:83], v[168:171], v[232:235], v[80:83]
	v_mfma_f32_16x16x32_bf16 v[68:71], v[160:163], v[240:243], v[68:71]
	v_mfma_f32_16x16x32_bf16 v[64:67], v[168:171], v[240:243], v[64:67]
	v_mfma_f32_16x16x32_bf16 v[116:119], v[164:167], v[220:223], v[116:119]
	v_mfma_f32_16x16x32_bf16 v[112:115], v[172:175], v[220:223], v[112:115]
	v_mfma_f32_16x16x32_bf16 v[100:103], v[164:167], v[228:231], v[100:103]
	v_mfma_f32_16x16x32_bf16 v[96:99], v[172:175], v[228:231], v[96:99]
	v_mfma_f32_16x16x32_bf16 v[84:87], v[164:167], v[236:239], v[84:87]
	v_mfma_f32_16x16x32_bf16 v[80:83], v[172:175], v[236:239], v[80:83]
	v_mfma_f32_16x16x32_bf16 v[68:71], v[164:167], v[244:247], v[68:71]
	v_mfma_f32_16x16x32_bf16 v[64:67], v[172:175], v[244:247], v[64:67]
	s_setprio 0
	s_barrier
	s_add_u32 s98, s36, 0x80
	s_addc_u32 s99, s37, 0
	s_add_u32 s100, s38, 0x80
	s_addc_u32 s101, s39, 0
	s_add_i32 s26, s52, s16
	s_mov_b32 m0, s26
	ds_read_b128 v[216:219], v204 offset:49152
	ds_read_b128 v[220:223], v204 offset:50176
	ds_read_b128 v[224:227], v204 offset:51200
	ds_read_b128 v[228:231], v204 offset:52224
	ds_read_b128 v[232:235], v204 offset:53248
	ds_read_b128 v[236:239], v204 offset:54272
	ds_read_b128 v[240:243], v204 offset:55296
	ds_read_b128 v[244:247], v204 offset:56320
	global_load_lds_dwordx4 v130, s[98:99]
	s_add_i32 m0, s26, 0x2000
	s_add_u32 s26, s36, 0xb0080
	s_addc_u32 s27, s37, 0
	s_add_i32 s36, s53, s16
	global_load_lds_dwordx4 v134, s[98:99]
	s_mov_b32 m0, s36
	s_nop 0
	global_load_lds_dwordx4 v130, s[26:27]
	s_add_i32 m0, s36, 0x2000
	s_nop 0
	global_load_lds_dwordx4 v134, s[26:27]
	s_mov_b32 m0, s41
	s_nop 0
	global_load_lds_dwordx4 v128, s[100:101]
	s_mov_b32 m0, s42
	s_nop 0
	global_load_lds_dwordx4 v132, s[100:101]
	s_waitcnt vmcnt(8)
	s_waitcnt lgkmcnt(0)
	s_barrier
	s_setprio 1
	s_waitcnt lgkmcnt(0)
	v_mfma_f32_16x16x32_bf16 v[60:63], v[144:147], v[216:219], v[60:63]
	v_mfma_f32_16x16x32_bf16 v[56:59], v[152:155], v[216:219], v[56:59]
	v_mfma_f32_16x16x32_bf16 v[44:47], v[144:147], v[224:227], v[44:47]
	v_mfma_f32_16x16x32_bf16 v[40:43], v[152:155], v[224:227], v[40:43]
	v_mfma_f32_16x16x32_bf16 v[28:31], v[144:147], v[232:235], v[28:31]
	v_mfma_f32_16x16x32_bf16 v[24:27], v[152:155], v[232:235], v[24:27]
	v_mfma_f32_16x16x32_bf16 v[12:15], v[144:147], v[240:243], v[12:15]
	v_mfma_f32_16x16x32_bf16 v[8:11], v[152:155], v[240:243], v[8:11]
	v_mfma_f32_16x16x32_bf16 v[60:63], v[148:151], v[220:223], v[60:63]
	v_mfma_f32_16x16x32_bf16 v[56:59], v[156:159], v[220:223], v[56:59]
	v_mfma_f32_16x16x32_bf16 v[44:47], v[148:151], v[228:231], v[44:47]
	v_mfma_f32_16x16x32_bf16 v[40:43], v[156:159], v[228:231], v[40:43]
	v_mfma_f32_16x16x32_bf16 v[28:31], v[148:151], v[236:239], v[28:31]
	v_mfma_f32_16x16x32_bf16 v[24:27], v[156:159], v[236:239], v[24:27]
	v_mfma_f32_16x16x32_bf16 v[12:15], v[148:151], v[244:247], v[12:15]
	v_mfma_f32_16x16x32_bf16 v[8:11], v[156:159], v[244:247], v[8:11]
	s_setprio 0
	s_setprio 1
	v_mfma_f32_16x16x32_bf16 v[52:55], v[160:163], v[216:219], v[52:55]
	v_mfma_f32_16x16x32_bf16 v[48:51], v[168:171], v[216:219], v[48:51]
	v_mfma_f32_16x16x32_bf16 v[36:39], v[160:163], v[224:227], v[36:39]
	v_mfma_f32_16x16x32_bf16 v[32:35], v[168:171], v[224:227], v[32:35]
	v_mfma_f32_16x16x32_bf16 v[20:23], v[160:163], v[232:235], v[20:23]
	v_mfma_f32_16x16x32_bf16 v[16:19], v[168:171], v[232:235], v[16:19]
	v_mfma_f32_16x16x32_bf16 v[4:7], v[160:163], v[240:243], v[4:7]
	v_mfma_f32_16x16x32_bf16 v[0:3], v[168:171], v[240:243], v[0:3]
	v_mfma_f32_16x16x32_bf16 v[52:55], v[164:167], v[220:223], v[52:55]
	v_mfma_f32_16x16x32_bf16 v[48:51], v[172:175], v[220:223], v[48:51]
	v_mfma_f32_16x16x32_bf16 v[36:39], v[164:167], v[228:231], v[36:39]
	v_mfma_f32_16x16x32_bf16 v[32:35], v[172:175], v[228:231], v[32:35]
	v_mfma_f32_16x16x32_bf16 v[20:23], v[164:167], v[236:239], v[20:23]
	v_mfma_f32_16x16x32_bf16 v[16:19], v[172:175], v[236:239], v[16:19]
	v_mfma_f32_16x16x32_bf16 v[4:7], v[164:167], v[244:247], v[4:7]
	v_mfma_f32_16x16x32_bf16 v[0:3], v[172:175], v[244:247], v[0:3]
	s_add_i32 s51, s51, 2
	s_add_u32 s25, s25, 0x100
	s_addc_u32 s50, s50, 0
	s_cmp_gt_u32 s51, 41
	s_mov_b64 s[26:27], s[34:35]
	s_setprio 0
	s_barrier
	s_cbranch_scc0 .LBB0_1433
	s_and_b64 vcc, exec, s[18:19]
	s_cbranch_vccz .LBB0_1436
	s_barrier
